# K-loops: per-phase s_setprio flips deleted, one static s_setprio 1 for waves 4-7 around each K-loop
# speedup vs baseline: 1.0001x; 1.0001x over previous
; #define PG8_STAGE(bufoff, gbase, voff) do { _Pragma("unroll") for (int _i = 0; _i < 2; ++_i) \
;         __builtin_amdgcn_global_load_lds((const unsigned*)((const char*)(gbase) + (voff)[_i]), (LAS unsigned*)(lds + (bufoff) + ldsw + _i * 8192), 16, 0, 0); } while (0)
; #define PG8_LDA(dst, b, h) do { _Pragma("unroll") for (int m = 0; m < 4; ++m) _Pragma("unroll") for (int k = 0; k < 2; ++k) dst[m][k] = *(const LAS bf16x8*)(lds + PG8_SA(b, h) + aoff + m * 2048 + k * 1024); } while (0)
; #define PG8_LDB(dst, b, h) do { _Pragma("unroll") for (int n = 0; n < 2; ++n) _Pragma("unroll") for (int k = 0; k < 2; ++k) dst[n][k] = *(const LAS bf16x8*)(lds + PG8_SB(b, h) + boff + n * 2048 + k * 1024); } while (0)
; #define PG8_MMA(ai, bj, At, Bt) do { __builtin_amdgcn_s_setprio(1); _Pragma("unroll") for (int m = 0; m < 4; ++m) _Pragma("unroll") for (int n = 0; n < 2; ++n) _Pragma("unroll") for (int k = 0; k < 2; ++k) \
;         acc[ai][bj][m][n] = __builtin_amdgcn_mfma_f32_16x16x32_bf16(Bt[n][k], At[m][k], acc[ai][bj][m][n], 0, 0, 0); __builtin_amdgcn_s_setprio(0); } while (0)
; template <class Epi, class Sched, bool ALIGN_EPI = true>
; __device__ __forceinline__ void gemm_phase(LAS unsigned char* lds, const Gemm g, const Sched& S, const Epi& E) {
;     ...
;         const bool has_next = S.next(ui + 1, nxt);
;         const char* nA = has_next ? (const char*)g.A + ((long)nxt.pm * g.mstride + g.moff) * (long)(g.lda * 2) : cA; const char* nB = has_next ? (const char*)g.Bt + (size_t)nxt.pn * tsB : cB;
;         for (int t = 0; t < nt; t += 2) {
;             const bool last = (t == nt - 2);
;             const char* a1 = cA + (size_t)(t + 1) * kstep;
;             const char* a2 = last ? nA : cA + (size_t)(t + 2) * kstep; const char* b2 = last ? nB : cB + (size_t)(t + 2) * kstep;
;             const char* a3 = a2 + kstep; const char* b3 = b2 + kstep;
;             PG8_LDB(B0, 0, 0); PG8_LDB(B1, 0, 1); PG8_SCHED; PG8_LDA(At, 0, 0); PG8_STAGE(PG8_SA(1, 1), a1 + hsA, voffA);
;             PG8_WAIT_V(8); PG8_WAIT_L(0); PG8_BAR; PG8_MMA(0, 0, At, B0); PG8_MMA(0, 1, At, B1); PG8_BAR; PG8_SCHED;
;     ...
;         for (int a = 0; a < 2; ++a)
; #pragma unroll
;             for (int b = 0; b < 2; ++b)
; #pragma unroll
;                 for (int m = 0; m < 4; ++m)
; #pragma unroll
;                     for (int n = 0; n < 2; ++n) acc[a][b][m][n] = (f32x4){0.f, 0.f, 0.f, 0.f};
.LBB0_133:
	s_ashr_i32 s17, s16, 31
	s_lshl_b64 s[20:21], s[16:17], 19
	v_readlane_b32 s58, v237, 50
	v_readlane_b32 s59, v237, 51
	s_add_u32 s20, s58, s20
	s_addc_u32 s21, s59, s21
	s_and_b64 s[4:5], s[4:5], exec
	s_cselect_b32 s3, s21, s7
	s_cselect_b32 s17, s20, s6
	s_add_u32 s4, s8, 0x40080
	s_addc_u32 s5, s9, 0
	s_add_u32 s23, s6, 0x100
	v_mov_b32_e32 v0, 0
	s_addc_u32 s33, s7, 0
	s_mov_b32 s58, -2
	v_mov_b32_e32 v1, v0
	v_mov_b32_e32 v2, v0
	v_mov_b32_e32 v3, v0
	v_mov_b32_e32 v4, v0
	v_mov_b32_e32 v5, v0
	v_mov_b32_e32 v6, v0
	v_mov_b32_e32 v7, v0
	v_mov_b32_e32 v16, v0
	v_mov_b32_e32 v17, v0
	v_mov_b32_e32 v18, v0
	v_mov_b32_e32 v19, v0
	v_mov_b32_e32 v20, v0
	v_mov_b32_e32 v21, v0
	v_mov_b32_e32 v22, v0
	v_mov_b32_e32 v23, v0
	v_mov_b32_e32 v32, v0
	v_mov_b32_e32 v33, v0
	v_mov_b32_e32 v34, v0
	v_mov_b32_e32 v35, v0
	v_mov_b32_e32 v36, v0
	v_mov_b32_e32 v37, v0
	v_mov_b32_e32 v38, v0
	v_mov_b32_e32 v39, v0
	v_mov_b32_e32 v48, v0
	v_mov_b32_e32 v49, v0
	v_mov_b32_e32 v50, v0
	v_mov_b32_e32 v51, v0
	v_mov_b32_e32 v52, v0
	v_mov_b32_e32 v53, v0
	v_mov_b32_e32 v54, v0
	v_mov_b32_e32 v55, v0
	v_mov_b32_e32 v8, v0
	v_mov_b32_e32 v9, v0
	v_mov_b32_e32 v10, v0
	v_mov_b32_e32 v11, v0
	v_mov_b32_e32 v12, v0
	v_mov_b32_e32 v13, v0
	v_mov_b32_e32 v14, v0
	v_mov_b32_e32 v15, v0
	v_mov_b32_e32 v24, v0
	v_mov_b32_e32 v25, v0
	v_mov_b32_e32 v26, v0
	v_mov_b32_e32 v27, v0
	v_mov_b32_e32 v28, v0
	v_mov_b32_e32 v29, v0
	v_mov_b32_e32 v30, v0
	v_mov_b32_e32 v31, v0
	v_mov_b32_e32 v40, v0
	v_mov_b32_e32 v41, v0
	v_mov_b32_e32 v42, v0
	v_mov_b32_e32 v43, v0
	v_mov_b32_e32 v44, v0
	v_mov_b32_e32 v45, v0
	v_mov_b32_e32 v46, v0
	v_mov_b32_e32 v47, v0
	v_mov_b32_e32 v56, v0
	v_mov_b32_e32 v57, v0
	v_mov_b32_e32 v58, v0
	v_mov_b32_e32 v59, v0
	v_mov_b32_e32 v60, v0
	v_mov_b32_e32 v61, v0
	v_mov_b32_e32 v62, v0
	v_mov_b32_e32 v63, v0
	v_mov_b32_e32 v64, v0
	v_mov_b32_e32 v65, v0
	v_mov_b32_e32 v66, v0
	v_mov_b32_e32 v67, v0
	v_mov_b32_e32 v68, v0
	v_mov_b32_e32 v69, v0
	v_mov_b32_e32 v70, v0
	v_mov_b32_e32 v71, v0
	v_mov_b32_e32 v80, v0
	v_mov_b32_e32 v81, v0
	v_mov_b32_e32 v82, v0
	v_mov_b32_e32 v83, v0
	v_mov_b32_e32 v84, v0
	v_mov_b32_e32 v85, v0
	v_mov_b32_e32 v86, v0
	v_mov_b32_e32 v87, v0
	v_mov_b32_e32 v96, v0
	v_mov_b32_e32 v97, v0
	v_mov_b32_e32 v98, v0
	v_mov_b32_e32 v99, v0
	v_mov_b32_e32 v100, v0
	v_mov_b32_e32 v101, v0
	v_mov_b32_e32 v102, v0
	v_mov_b32_e32 v103, v0
	v_mov_b32_e32 v112, v0
	v_mov_b32_e32 v113, v0
	v_mov_b32_e32 v114, v0
	v_mov_b32_e32 v115, v0
	v_mov_b32_e32 v116, v0
	v_mov_b32_e32 v117, v0
	v_mov_b32_e32 v118, v0
	v_mov_b32_e32 v119, v0
	v_mov_b32_e32 v72, v0
	v_mov_b32_e32 v73, v0
	v_mov_b32_e32 v74, v0
	v_mov_b32_e32 v75, v0
	v_mov_b32_e32 v76, v0
	v_mov_b32_e32 v77, v0
	v_mov_b32_e32 v78, v0
	v_mov_b32_e32 v79, v0
	v_mov_b32_e32 v88, v0
	v_mov_b32_e32 v89, v0
	v_mov_b32_e32 v90, v0
	v_mov_b32_e32 v91, v0
	v_mov_b32_e32 v92, v0
	v_mov_b32_e32 v93, v0
	v_mov_b32_e32 v94, v0
	v_mov_b32_e32 v95, v0
	v_mov_b32_e32 v104, v0
	v_mov_b32_e32 v105, v0
	v_mov_b32_e32 v106, v0
	v_mov_b32_e32 v107, v0
	v_mov_b32_e32 v108, v0
	v_mov_b32_e32 v109, v0
	v_mov_b32_e32 v110, v0
	v_mov_b32_e32 v111, v0
	v_mov_b32_e32 v120, v0
	v_mov_b32_e32 v121, v0
	v_mov_b32_e32 v122, v0
	v_mov_b32_e32 v123, v0
	v_mov_b32_e32 v124, v0
	v_mov_b32_e32 v125, v0
	v_mov_b32_e32 v126, v0
	v_mov_b32_e32 v127, v0
	v_readfirstlane_b32 s98, v181
	s_lshr_b32 s98, s98, 8
	s_cmp_eq_u32 s98, 0
	s_cbranch_scc1 .LprioK1
	s_setprio 1
.LprioK1:
.LBB0_134:
	ds_read_b128 v[146:149], v158
	ds_read_b128 v[162:165], v158 offset:1024
	ds_read_b128 v[166:169], v158 offset:2048
	ds_read_b128 v[170:173], v158 offset:3072
	ds_read_b128 v[174:177], v159
	ds_read_b128 v[182:185], v159 offset:1024
	ds_read_b128 v[186:189], v159 offset:2048
	ds_read_b128 v[190:193], v159 offset:3072
	s_add_u32 s6, s4, 0xfffc0080
	s_addc_u32 s7, s5, -1
	s_cmp_eq_u32 s58, 12
	s_cselect_b32 s9, s19, s7
	s_cselect_b32 s8, s18, s6
	s_cselect_b32 s7, s3, s33
	s_cselect_b32 s6, s17, s23
	v_lshl_add_u64 v[150:151], s[4:5], 0, v[138:139]
	s_add_i32 m0, s25, 0xc000
	ds_read_b128 v[194:197], v160
	ds_read_b128 v[198:201], v160 offset:1024
	ds_read_b128 v[202:205], v160 offset:2048
	ds_read_b128 v[206:209], v160 offset:3072
	ds_read_b128 v[210:213], v160 offset:4096
	ds_read_b128 v[214:217], v160 offset:5120
	ds_read_b128 v[218:221], v160 offset:6144
	ds_read_b128 v[222:225], v160 offset:7168
	global_load_lds_dwordx4 v[150:151], off
	v_lshl_add_u64 v[150:151], s[4:5], 0, v[140:141]
	s_add_i32 m0, s25, 0xe000
	s_nop 0
	global_load_lds_dwordx4 v[150:151], off
	s_waitcnt vmcnt(8)
	s_waitcnt lgkmcnt(0)
	s_barrier
; #define PG8_STAGE(bufoff, gbase, voff) do { _Pragma("unroll") for (int _i = 0; _i < 2; ++_i) \
;         __builtin_amdgcn_global_load_lds((const unsigned*)((const char*)(gbase) + (voff)[_i]), (LAS unsigned*)(lds + (bufoff) + ldsw + _i * 8192), 16, 0, 0); } while (0)
; #define PG8_LDA(dst, b, h) do { _Pragma("unroll") for (int m = 0; m < 4; ++m) _Pragma("unroll") for (int k = 0; k < 2; ++k) dst[m][k] = *(const LAS bf16x8*)(lds + PG8_SA(b, h) + aoff + m * 2048 + k * 1024); } while (0)
; #define PG8_MMA(ai, bj, At, Bt) do { __builtin_amdgcn_s_setprio(1); _Pragma("unroll") for (int m = 0; m < 4; ++m) _Pragma("unroll") for (int n = 0; n < 2; ++n) _Pragma("unroll") for (int k = 0; k < 2; ++k) \
;         acc[ai][bj][m][n] = __builtin_amdgcn_mfma_f32_16x16x32_bf16(Bt[n][k], At[m][k], acc[ai][bj][m][n], 0, 0, 0); __builtin_amdgcn_s_setprio(0); } while (0)
; #define PG8_WAIT_V(n) asm volatile("s_waitcnt vmcnt(" #n ")" ::: "memory")
; #define PG8_WAIT_L(n) asm volatile("s_waitcnt lgkmcnt(" #n ")" ::: "memory")
; #define PG8_BAR __builtin_amdgcn_s_barrier()
; #define PG8_SCHED __builtin_amdgcn_sched_barrier(0)
; template <class Epi, class Sched, bool ALIGN_EPI = true>
; __device__ __forceinline__ void gemm_phase(LAS unsigned char* lds, const Gemm g, const Sched& S, const Epi& E) {
;     ...
;             PG8_WAIT_V(8); PG8_WAIT_L(0); PG8_BAR; PG8_MMA(0, 0, At, B0); PG8_MMA(0, 1, At, B1); PG8_BAR; PG8_SCHED;
;             PG8_LDA(At, 0, 1); PG8_STAGE(PG8_SB(0, 0), b2, voffB); PG8_STAGE(PG8_SB(0, 1), b2 + hsB, voffB); PG8_STAGE(PG8_SA(0, 0), a2, voffA);
;             PG8_WAIT_V(8); PG8_WAIT_L(0); PG8_BAR; PG8_MMA(1, 0, At, B0); PG8_MMA(1, 1, At, B1); PG8_BAR; PG8_SCHED;
	s_waitcnt lgkmcnt(0)
	v_mfma_f32_16x16x32_bf16 v[124:127], v[146:149], v[194:197], v[124:127]
	v_mfma_f32_16x16x32_bf16 v[120:123], v[166:169], v[194:197], v[120:123]
	v_mfma_f32_16x16x32_bf16 v[108:111], v[146:149], v[202:205], v[108:111]
	v_mfma_f32_16x16x32_bf16 v[104:107], v[166:169], v[202:205], v[104:107]
	v_mfma_f32_16x16x32_bf16 v[92:95], v[146:149], v[210:213], v[92:95]
	v_mfma_f32_16x16x32_bf16 v[88:91], v[166:169], v[210:213], v[88:91]
	v_mfma_f32_16x16x32_bf16 v[76:79], v[146:149], v[218:221], v[76:79]
	v_mfma_f32_16x16x32_bf16 v[72:75], v[166:169], v[218:221], v[72:75]
	v_mfma_f32_16x16x32_bf16 v[124:127], v[162:165], v[198:201], v[124:127]
	v_mfma_f32_16x16x32_bf16 v[120:123], v[170:173], v[198:201], v[120:123]
	v_mfma_f32_16x16x32_bf16 v[108:111], v[162:165], v[206:209], v[108:111]
	v_mfma_f32_16x16x32_bf16 v[104:107], v[170:173], v[206:209], v[104:107]
	v_mfma_f32_16x16x32_bf16 v[92:95], v[162:165], v[214:217], v[92:95]
	v_mfma_f32_16x16x32_bf16 v[88:91], v[170:173], v[214:217], v[88:91]
	v_mfma_f32_16x16x32_bf16 v[76:79], v[162:165], v[222:225], v[76:79]
	v_mfma_f32_16x16x32_bf16 v[72:75], v[170:173], v[222:225], v[72:75]
	v_mfma_f32_16x16x32_bf16 v[116:119], v[174:177], v[194:197], v[116:119]
	v_mfma_f32_16x16x32_bf16 v[112:115], v[186:189], v[194:197], v[112:115]
	v_mfma_f32_16x16x32_bf16 v[100:103], v[174:177], v[202:205], v[100:103]
	v_mfma_f32_16x16x32_bf16 v[96:99], v[186:189], v[202:205], v[96:99]
	v_mfma_f32_16x16x32_bf16 v[84:87], v[174:177], v[210:213], v[84:87]
	v_mfma_f32_16x16x32_bf16 v[80:83], v[186:189], v[210:213], v[80:83]
	v_mfma_f32_16x16x32_bf16 v[68:71], v[174:177], v[218:221], v[68:71]
	v_mfma_f32_16x16x32_bf16 v[64:67], v[186:189], v[218:221], v[64:67]
	v_mfma_f32_16x16x32_bf16 v[116:119], v[182:185], v[198:201], v[116:119]
	v_mfma_f32_16x16x32_bf16 v[112:115], v[190:193], v[198:201], v[112:115]
	v_mfma_f32_16x16x32_bf16 v[100:103], v[182:185], v[206:209], v[100:103]
	v_mfma_f32_16x16x32_bf16 v[96:99], v[190:193], v[206:209], v[96:99]
	v_mfma_f32_16x16x32_bf16 v[84:87], v[182:185], v[214:217], v[84:87]
	v_mfma_f32_16x16x32_bf16 v[80:83], v[190:193], v[214:217], v[80:83]
	v_mfma_f32_16x16x32_bf16 v[68:71], v[182:185], v[222:225], v[68:71]
	v_mfma_f32_16x16x32_bf16 v[64:67], v[190:193], v[222:225], v[64:67]
	s_barrier
	s_add_i32 s59, s48, s24
	v_lshl_add_u64 v[150:151], s[6:7], 0, v[130:131]
	s_mov_b32 m0, s59
	ds_read_b128 v[194:197], v160 offset:16384
	ds_read_b128 v[198:201], v160 offset:17408
	ds_read_b128 v[202:205], v160 offset:18432
	ds_read_b128 v[206:209], v160 offset:19456
	ds_read_b128 v[210:213], v160 offset:20480
	ds_read_b128 v[214:217], v160 offset:21504
	ds_read_b128 v[218:221], v160 offset:22528
	ds_read_b128 v[222:225], v160 offset:23552
	global_load_lds_dwordx4 v[150:151], off
	s_add_i32 m0, s59, 0x2000
	s_add_u32 s60, s6, 0x40000
	v_lshl_add_u64 v[178:179], s[6:7], 0, v[134:135]
	s_addc_u32 s61, s7, 0
	s_add_i32 s59, s49, s24
	global_load_lds_dwordx4 v[178:179], off
	v_lshl_add_u64 v[226:227], s[60:61], 0, v[130:131]
	s_mov_b32 m0, s59
	v_lshl_add_u64 v[228:229], s[8:9], 0, v[132:133]
	global_load_lds_dwordx4 v[226:227], off
	v_lshl_add_u64 v[226:227], s[60:61], 0, v[134:135]
	s_add_i32 m0, s59, 0x2000
	s_nop 0
	global_load_lds_dwordx4 v[226:227], off
	v_lshl_add_u64 v[226:227], s[8:9], 0, v[128:129]
	s_mov_b32 m0, s25
	s_nop 0
	global_load_lds_dwordx4 v[226:227], off
	s_mov_b32 m0, s26
	s_nop 0
	global_load_lds_dwordx4 v[228:229], off
	s_waitcnt vmcnt(8)
	s_waitcnt lgkmcnt(0)
	s_barrier
	s_waitcnt lgkmcnt(0)
	v_mfma_f32_16x16x32_bf16 v[60:63], v[146:149], v[194:197], v[60:63]
	v_mfma_f32_16x16x32_bf16 v[56:59], v[166:169], v[194:197], v[56:59]
	v_mfma_f32_16x16x32_bf16 v[44:47], v[146:149], v[202:205], v[44:47]
	v_mfma_f32_16x16x32_bf16 v[40:43], v[166:169], v[202:205], v[40:43]
	v_mfma_f32_16x16x32_bf16 v[28:31], v[146:149], v[210:213], v[28:31]
	v_mfma_f32_16x16x32_bf16 v[24:27], v[166:169], v[210:213], v[24:27]
	v_mfma_f32_16x16x32_bf16 v[12:15], v[146:149], v[218:221], v[12:15]
	v_mfma_f32_16x16x32_bf16 v[8:11], v[166:169], v[218:221], v[8:11]
	v_mfma_f32_16x16x32_bf16 v[60:63], v[162:165], v[198:201], v[60:63]
	v_mfma_f32_16x16x32_bf16 v[56:59], v[170:173], v[198:201], v[56:59]
	v_mfma_f32_16x16x32_bf16 v[44:47], v[162:165], v[206:209], v[44:47]
	v_mfma_f32_16x16x32_bf16 v[40:43], v[170:173], v[206:209], v[40:43]
	v_mfma_f32_16x16x32_bf16 v[28:31], v[162:165], v[214:217], v[28:31]
	v_mfma_f32_16x16x32_bf16 v[24:27], v[170:173], v[214:217], v[24:27]
	v_mfma_f32_16x16x32_bf16 v[12:15], v[162:165], v[222:225], v[12:15]
	v_mfma_f32_16x16x32_bf16 v[8:11], v[170:173], v[222:225], v[8:11]
	v_mfma_f32_16x16x32_bf16 v[52:55], v[174:177], v[194:197], v[52:55]
	v_mfma_f32_16x16x32_bf16 v[48:51], v[186:189], v[194:197], v[48:51]
	v_mfma_f32_16x16x32_bf16 v[36:39], v[174:177], v[202:205], v[36:39]
	v_mfma_f32_16x16x32_bf16 v[32:35], v[186:189], v[202:205], v[32:35]
	v_mfma_f32_16x16x32_bf16 v[20:23], v[174:177], v[210:213], v[20:23]
	v_mfma_f32_16x16x32_bf16 v[16:19], v[186:189], v[210:213], v[16:19]
	v_mfma_f32_16x16x32_bf16 v[4:7], v[174:177], v[218:221], v[4:7]
	v_mfma_f32_16x16x32_bf16 v[0:3], v[186:189], v[218:221], v[0:3]
	v_mfma_f32_16x16x32_bf16 v[52:55], v[182:185], v[198:201], v[52:55]
	v_mfma_f32_16x16x32_bf16 v[48:51], v[190:193], v[198:201], v[48:51]
	v_mfma_f32_16x16x32_bf16 v[36:39], v[182:185], v[206:209], v[36:39]
	v_mfma_f32_16x16x32_bf16 v[32:35], v[190:193], v[206:209], v[32:35]
	v_mfma_f32_16x16x32_bf16 v[20:23], v[182:185], v[214:217], v[20:23]
	v_mfma_f32_16x16x32_bf16 v[16:19], v[190:193], v[214:217], v[16:19]
	v_mfma_f32_16x16x32_bf16 v[4:7], v[182:185], v[222:225], v[4:7]
	v_mfma_f32_16x16x32_bf16 v[0:3], v[190:193], v[222:225], v[0:3]
	s_barrier
; #define PG8_STAGE(bufoff, gbase, voff) do { _Pragma("unroll") for (int _i = 0; _i < 2; ++_i) \
;         __builtin_amdgcn_global_load_lds((const unsigned*)((const char*)(gbase) + (voff)[_i]), (LAS unsigned*)(lds + (bufoff) + ldsw + _i * 8192), 16, 0, 0); } while (0)
; #define PG8_LDA(dst, b, h) do { _Pragma("unroll") for (int m = 0; m < 4; ++m) _Pragma("unroll") for (int k = 0; k < 2; ++k) dst[m][k] = *(const LAS bf16x8*)(lds + PG8_SA(b, h) + aoff + m * 2048 + k * 1024); } while (0)
; #define PG8_LDB(dst, b, h) do { _Pragma("unroll") for (int n = 0; n < 2; ++n) _Pragma("unroll") for (int k = 0; k < 2; ++k) dst[n][k] = *(const LAS bf16x8*)(lds + PG8_SB(b, h) + boff + n * 2048 + k * 1024); } while (0)
; #define PG8_MMA(ai, bj, At, Bt) do { __builtin_amdgcn_s_setprio(1); _Pragma("unroll") for (int m = 0; m < 4; ++m) _Pragma("unroll") for (int n = 0; n < 2; ++n) _Pragma("unroll") for (int k = 0; k < 2; ++k) \
;         acc[ai][bj][m][n] = __builtin_amdgcn_mfma_f32_16x16x32_bf16(Bt[n][k], At[m][k], acc[ai][bj][m][n], 0, 0, 0); __builtin_amdgcn_s_setprio(0); } while (0)
; #define PG8_WAIT_V(n) asm volatile("s_waitcnt vmcnt(" #n ")" ::: "memory")
; #define PG8_WAIT_L(n) asm volatile("s_waitcnt lgkmcnt(" #n ")" ::: "memory")
; #define PG8_BAR __builtin_amdgcn_s_barrier()
; #define PG8_SCHED __builtin_amdgcn_sched_barrier(0)
; template <class Epi, class Sched, bool ALIGN_EPI = true>
; __device__ __forceinline__ void gemm_phase(LAS unsigned char* lds, const Gemm g, const Sched& S, const Epi& E) {
;     ...
;             PG8_LDB(B0, 1, 0); PG8_LDB(B1, 1, 1); PG8_SCHED; PG8_LDA(At, 1, 0); PG8_STAGE(PG8_SA(0, 1), a2 + hsA, voffA);
;             PG8_WAIT_V(8); PG8_WAIT_L(0); PG8_BAR; PG8_MMA(0, 0, At, B0); PG8_MMA(0, 1, At, B1); PG8_BAR; PG8_SCHED;
	s_add_i32 s59, 0, 0x18000
	v_add_u32_e32 v136, s59, v156
	s_add_i32 s60, 0, 0x1c000
	ds_read_b128 v[146:149], v136
	ds_read_b128 v[162:165], v136 offset:1024
	ds_read_b128 v[166:169], v136 offset:2048
	ds_read_b128 v[170:173], v136 offset:3072
	v_add_u32_e32 v136, s60, v156
	ds_read_b128 v[174:177], v136
	ds_read_b128 v[182:185], v136 offset:1024
	ds_read_b128 v[186:189], v136 offset:2048
	ds_read_b128 v[190:193], v136 offset:3072
	s_add_u32 s8, s8, 0x40000
	s_addc_u32 s9, s9, 0
	s_mov_b32 m0, s27
	v_lshl_add_u64 v[230:231], s[8:9], 0, v[128:129]
	ds_read_b128 v[194:197], v160 offset:32768
	ds_read_b128 v[198:201], v160 offset:33792
	ds_read_b128 v[202:205], v160 offset:34816
	ds_read_b128 v[206:209], v160 offset:35840
	ds_read_b128 v[210:213], v160 offset:36864
	ds_read_b128 v[214:217], v160 offset:37888
	ds_read_b128 v[218:221], v160 offset:38912
	ds_read_b128 v[222:225], v160 offset:39936
	global_load_lds_dwordx4 v[230:231], off
	v_lshl_add_u64 v[230:231], s[8:9], 0, v[132:133]
	s_mov_b32 m0, s28
	s_nop 0
	global_load_lds_dwordx4 v[230:231], off
	s_waitcnt vmcnt(8)
	s_waitcnt lgkmcnt(0)
	s_barrier
	s_waitcnt lgkmcnt(0)
	v_mfma_f32_16x16x32_bf16 v[124:127], v[146:149], v[194:197], v[124:127]
	v_mfma_f32_16x16x32_bf16 v[120:123], v[166:169], v[194:197], v[120:123]
	v_mfma_f32_16x16x32_bf16 v[108:111], v[146:149], v[202:205], v[108:111]
	v_mfma_f32_16x16x32_bf16 v[104:107], v[166:169], v[202:205], v[104:107]
	v_mfma_f32_16x16x32_bf16 v[92:95], v[146:149], v[210:213], v[92:95]
	v_mfma_f32_16x16x32_bf16 v[88:91], v[166:169], v[210:213], v[88:91]
	v_mfma_f32_16x16x32_bf16 v[76:79], v[146:149], v[218:221], v[76:79]
	v_mfma_f32_16x16x32_bf16 v[72:75], v[166:169], v[218:221], v[72:75]
	v_mfma_f32_16x16x32_bf16 v[124:127], v[162:165], v[198:201], v[124:127]
	v_mfma_f32_16x16x32_bf16 v[120:123], v[170:173], v[198:201], v[120:123]
	v_mfma_f32_16x16x32_bf16 v[108:111], v[162:165], v[206:209], v[108:111]
	v_mfma_f32_16x16x32_bf16 v[104:107], v[170:173], v[206:209], v[104:107]
	v_mfma_f32_16x16x32_bf16 v[92:95], v[162:165], v[214:217], v[92:95]
	v_mfma_f32_16x16x32_bf16 v[88:91], v[170:173], v[214:217], v[88:91]
	v_mfma_f32_16x16x32_bf16 v[76:79], v[162:165], v[222:225], v[76:79]
	v_mfma_f32_16x16x32_bf16 v[72:75], v[170:173], v[222:225], v[72:75]
	v_mfma_f32_16x16x32_bf16 v[116:119], v[174:177], v[194:197], v[116:119]
	v_mfma_f32_16x16x32_bf16 v[112:115], v[186:189], v[194:197], v[112:115]
	v_mfma_f32_16x16x32_bf16 v[100:103], v[174:177], v[202:205], v[100:103]
	v_mfma_f32_16x16x32_bf16 v[96:99], v[186:189], v[202:205], v[96:99]
	v_mfma_f32_16x16x32_bf16 v[84:87], v[174:177], v[210:213], v[84:87]
	v_mfma_f32_16x16x32_bf16 v[80:83], v[186:189], v[210:213], v[80:83]
	v_mfma_f32_16x16x32_bf16 v[68:71], v[174:177], v[218:221], v[68:71]
	v_mfma_f32_16x16x32_bf16 v[64:67], v[186:189], v[218:221], v[64:67]
	v_mfma_f32_16x16x32_bf16 v[116:119], v[182:185], v[198:201], v[116:119]
	v_mfma_f32_16x16x32_bf16 v[112:115], v[190:193], v[198:201], v[112:115]
	v_mfma_f32_16x16x32_bf16 v[100:103], v[182:185], v[206:209], v[100:103]
	v_mfma_f32_16x16x32_bf16 v[96:99], v[190:193], v[206:209], v[96:99]
	v_mfma_f32_16x16x32_bf16 v[84:87], v[182:185], v[214:217], v[84:87]
	v_mfma_f32_16x16x32_bf16 v[80:83], v[190:193], v[214:217], v[80:83]
	v_mfma_f32_16x16x32_bf16 v[68:71], v[182:185], v[222:225], v[68:71]
	v_mfma_f32_16x16x32_bf16 v[64:67], v[190:193], v[222:225], v[64:67]
	s_barrier
; #define PG8_STAGE(bufoff, gbase, voff) do { _Pragma("unroll") for (int _i = 0; _i < 2; ++_i) \
;         __builtin_amdgcn_global_load_lds((const unsigned*)((const char*)(gbase) + (voff)[_i]), (LAS unsigned*)(lds + (bufoff) + ldsw + _i * 8192), 16, 0, 0); } while (0)
; #define PG8_LDA(dst, b, h) do { _Pragma("unroll") for (int m = 0; m < 4; ++m) _Pragma("unroll") for (int k = 0; k < 2; ++k) dst[m][k] = *(const LAS bf16x8*)(lds + PG8_SA(b, h) + aoff + m * 2048 + k * 1024); } while (0)
; #define PG8_MMA(ai, bj, At, Bt) do { __builtin_amdgcn_s_setprio(1); _Pragma("unroll") for (int m = 0; m < 4; ++m) _Pragma("unroll") for (int n = 0; n < 2; ++n) _Pragma("unroll") for (int k = 0; k < 2; ++k) \
;         acc[ai][bj][m][n] = __builtin_amdgcn_mfma_f32_16x16x32_bf16(Bt[n][k], At[m][k], acc[ai][bj][m][n], 0, 0, 0); __builtin_amdgcn_s_setprio(0); } while (0)
; #define PG8_WAIT_V(n) asm volatile("s_waitcnt vmcnt(" #n ")" ::: "memory")
; #define PG8_WAIT_L(n) asm volatile("s_waitcnt lgkmcnt(" #n ")" ::: "memory")
; #define PG8_BAR __builtin_amdgcn_s_barrier()
; #define PG8_SCHED __builtin_amdgcn_sched_barrier(0)
; template <class Epi, class Sched, bool ALIGN_EPI = true>
; __device__ __forceinline__ void gemm_phase(LAS unsigned char* lds, const Gemm g, const Sched& S, const Epi& E) {
;     ...
;             PG8_LDA(At, 1, 1); PG8_STAGE(PG8_SB(1, 0), b3, voffB); PG8_STAGE(PG8_SB(1, 1), b3 + hsB, voffB); PG8_STAGE(PG8_SA(1, 0), a3, voffA);
;             PG8_WAIT_V(8); PG8_WAIT_L(0); PG8_BAR; PG8_MMA(1, 0, At, B0); PG8_MMA(1, 1, At, B1); PG8_BAR; PG8_SCHED;
;         }
;         if constexpr (ALIGN_EPI) { if (wr == 0) PG8_BAR; }
	s_add_i32 s8, s59, s24
	v_lshl_add_u64 v[150:151], v[150:151], 0, s[12:13]
	s_mov_b32 m0, s8
	ds_read_b128 v[194:197], v160 offset:49152
	ds_read_b128 v[198:201], v160 offset:50176
	ds_read_b128 v[202:205], v160 offset:51200
	ds_read_b128 v[206:209], v160 offset:52224
	ds_read_b128 v[210:213], v160 offset:53248
	ds_read_b128 v[214:217], v160 offset:54272
	ds_read_b128 v[218:221], v160 offset:55296
	ds_read_b128 v[222:225], v160 offset:56320
	global_load_lds_dwordx4 v[150:151], off
	s_add_i32 m0, s8, 0x2000
	s_add_u32 s6, s6, 0x40080
	v_lshl_add_u64 v[150:151], v[178:179], 0, s[12:13]
	s_addc_u32 s7, s7, 0
	s_add_i32 s8, s60, s24
	global_load_lds_dwordx4 v[150:151], off
	v_lshl_add_u64 v[150:151], s[6:7], 0, v[130:131]
	s_mov_b32 m0, s8
	s_nop 0
	global_load_lds_dwordx4 v[150:151], off
	v_lshl_add_u64 v[150:151], s[6:7], 0, v[134:135]
	s_add_i32 m0, s8, 0x2000
	s_nop 0
	global_load_lds_dwordx4 v[150:151], off
	v_lshl_add_u64 v[150:151], v[226:227], 0, s[12:13]
	s_mov_b32 m0, s31
	s_nop 0
	global_load_lds_dwordx4 v[150:151], off
	v_lshl_add_u64 v[150:151], v[228:229], 0, s[12:13]
	s_mov_b32 m0, s34
	s_nop 0
	global_load_lds_dwordx4 v[150:151], off
	s_waitcnt vmcnt(8)
	s_waitcnt lgkmcnt(0)
	s_barrier
	s_waitcnt lgkmcnt(0)
	v_mfma_f32_16x16x32_bf16 v[60:63], v[146:149], v[194:197], v[60:63]
	v_mfma_f32_16x16x32_bf16 v[56:59], v[166:169], v[194:197], v[56:59]
	v_mfma_f32_16x16x32_bf16 v[44:47], v[146:149], v[202:205], v[44:47]
	v_mfma_f32_16x16x32_bf16 v[40:43], v[166:169], v[202:205], v[40:43]
	v_mfma_f32_16x16x32_bf16 v[28:31], v[146:149], v[210:213], v[28:31]
	v_mfma_f32_16x16x32_bf16 v[24:27], v[166:169], v[210:213], v[24:27]
	v_mfma_f32_16x16x32_bf16 v[12:15], v[146:149], v[218:221], v[12:15]
	v_mfma_f32_16x16x32_bf16 v[8:11], v[166:169], v[218:221], v[8:11]
	v_mfma_f32_16x16x32_bf16 v[60:63], v[162:165], v[198:201], v[60:63]
	v_mfma_f32_16x16x32_bf16 v[56:59], v[170:173], v[198:201], v[56:59]
	v_mfma_f32_16x16x32_bf16 v[44:47], v[162:165], v[206:209], v[44:47]
	v_mfma_f32_16x16x32_bf16 v[40:43], v[170:173], v[206:209], v[40:43]
	v_mfma_f32_16x16x32_bf16 v[28:31], v[162:165], v[214:217], v[28:31]
	v_mfma_f32_16x16x32_bf16 v[24:27], v[170:173], v[214:217], v[24:27]
	v_mfma_f32_16x16x32_bf16 v[12:15], v[162:165], v[222:225], v[12:15]
	v_mfma_f32_16x16x32_bf16 v[8:11], v[170:173], v[222:225], v[8:11]
	v_mfma_f32_16x16x32_bf16 v[52:55], v[174:177], v[194:197], v[52:55]
	v_mfma_f32_16x16x32_bf16 v[48:51], v[186:189], v[194:197], v[48:51]
	v_mfma_f32_16x16x32_bf16 v[36:39], v[174:177], v[202:205], v[36:39]
	v_mfma_f32_16x16x32_bf16 v[32:35], v[186:189], v[202:205], v[32:35]
	v_mfma_f32_16x16x32_bf16 v[20:23], v[174:177], v[210:213], v[20:23]
	v_mfma_f32_16x16x32_bf16 v[16:19], v[186:189], v[210:213], v[16:19]
	v_mfma_f32_16x16x32_bf16 v[4:7], v[174:177], v[218:221], v[4:7]
	v_mfma_f32_16x16x32_bf16 v[0:3], v[186:189], v[218:221], v[0:3]
	v_mfma_f32_16x16x32_bf16 v[52:55], v[182:185], v[198:201], v[52:55]
	v_mfma_f32_16x16x32_bf16 v[48:51], v[190:193], v[198:201], v[48:51]
	v_mfma_f32_16x16x32_bf16 v[36:39], v[182:185], v[206:209], v[36:39]
	v_mfma_f32_16x16x32_bf16 v[32:35], v[190:193], v[206:209], v[32:35]
	v_mfma_f32_16x16x32_bf16 v[20:23], v[182:185], v[214:217], v[20:23]
	v_mfma_f32_16x16x32_bf16 v[16:19], v[190:193], v[214:217], v[16:19]
	v_mfma_f32_16x16x32_bf16 v[4:7], v[182:185], v[222:225], v[4:7]
	v_mfma_f32_16x16x32_bf16 v[0:3], v[190:193], v[222:225], v[0:3]
	s_barrier
	s_add_i32 s58, s58, 2
	s_add_u32 s4, s4, 0x100
	s_addc_u32 s5, s5, 0
	s_add_u32 s23, s23, 0x100
	s_addc_u32 s33, s33, 0
	s_cmp_gt_u32 s58, 13
	s_cbranch_scc0 .LBB0_134
	s_setprio 0
	s_and_b64 vcc, exec, s[14:15]
	s_cbranch_vccz .LBB0_137
	s_barrier

; #define PG8_STAGE(bufoff, gbase, voff) do { _Pragma("unroll") for (int _i = 0; _i < 2; ++_i) \
;         __builtin_amdgcn_global_load_lds((const unsigned*)((const char*)(gbase) + (voff)[_i]), (LAS unsigned*)(lds + (bufoff) + ldsw + _i * 8192), 16, 0, 0); } while (0)
; #define PG8_LDA(dst, b, h) do { _Pragma("unroll") for (int m = 0; m < 4; ++m) _Pragma("unroll") for (int k = 0; k < 2; ++k) dst[m][k] = *(const LAS bf16x8*)(lds + PG8_SA(b, h) + aoff + m * 2048 + k * 1024); } while (0)
; #define PG8_LDB(dst, b, h) do { _Pragma("unroll") for (int n = 0; n < 2; ++n) _Pragma("unroll") for (int k = 0; k < 2; ++k) dst[n][k] = *(const LAS bf16x8*)(lds + PG8_SB(b, h) + boff + n * 2048 + k * 1024); } while (0)
; #define PG8_MMA(ai, bj, At, Bt) do { __builtin_amdgcn_s_setprio(1); _Pragma("unroll") for (int m = 0; m < 4; ++m) _Pragma("unroll") for (int n = 0; n < 2; ++n) _Pragma("unroll") for (int k = 0; k < 2; ++k) \
;         acc[ai][bj][m][n] = __builtin_amdgcn_mfma_f32_16x16x32_bf16(Bt[n][k], At[m][k], acc[ai][bj][m][n], 0, 0, 0); __builtin_amdgcn_s_setprio(0); } while (0)
; template <class Epi, class Sched, bool ALIGN_EPI = true>
; __device__ __forceinline__ void gemm_phase(LAS unsigned char* lds, const Gemm g, const Sched& S, const Epi& E) {
;     ...
;         const bool has_next = S.next(ui + 1, nxt);
;         const char* nA = has_next ? (const char*)g.A + ((long)nxt.pm * g.mstride + g.moff) * (long)(g.lda * 2) : cA; const char* nB = has_next ? (const char*)g.Bt + (size_t)nxt.pn * tsB : cB;
;         for (int t = 0; t < nt; t += 2) {
;             const bool last = (t == nt - 2);
;             const char* a1 = cA + (size_t)(t + 1) * kstep;
;             const char* a2 = last ? nA : cA + (size_t)(t + 2) * kstep; const char* b2 = last ? nB : cB + (size_t)(t + 2) * kstep;
;             const char* a3 = a2 + kstep; const char* b3 = b2 + kstep;
;             PG8_LDB(B0, 0, 0); PG8_LDB(B1, 0, 1); PG8_SCHED; PG8_LDA(At, 0, 0); PG8_STAGE(PG8_SA(1, 1), a1 + hsA, voffA);
;             PG8_WAIT_V(8); PG8_WAIT_L(0); PG8_BAR; PG8_MMA(0, 0, At, B0); PG8_MMA(0, 1, At, B1); PG8_BAR; PG8_SCHED;
;     ...
;         for (int a = 0; a < 2; ++a)
; #pragma unroll
;             for (int b = 0; b < 2; ++b)
; #pragma unroll
;                 for (int m = 0; m < 4; ++m)
; #pragma unroll
;                     for (int n = 0; n < 2; ++n) acc[a][b][m][n] = (f32x4){0.f, 0.f, 0.f, 0.f};
.LBB0_703:
	s_ashr_i32 s27, s26, 31
	s_lshl_b64 s[28:29], s[26:27], 20
	v_readlane_b32 s30, v237, 58
	v_readlane_b32 s31, v237, 59
	s_add_u32 s28, s30, s28
	s_addc_u32 s29, s31, s29
	s_and_b64 s[30:31], s[6:7], exec
	s_cselect_b32 s9, s29, s37
	s_cselect_b32 s27, s28, s36
	s_ashr_i32 s25, s24, 31
	s_lshl_b64 s[30:31], s[24:25], 20
	v_readlane_b32 s40, v237, 52
	v_readlane_b32 s41, v237, 53
	s_add_u32 s30, s40, s30
	s_addc_u32 s31, s41, s31
	s_and_b64 s[40:41], s[6:7], exec
	s_cselect_b32 s25, s31, s39
	s_cselect_b32 s35, s30, s38
	s_add_u32 s36, s36, 0x80080
	s_addc_u32 s37, s37, 0
	s_add_u32 s55, s38, 0x100
	v_mov_b32_e32 v0, 0
	s_addc_u32 s56, s39, 0
	s_mov_b32 s57, -2
	v_mov_b32_e32 v1, v0
	v_mov_b32_e32 v2, v0
	v_mov_b32_e32 v3, v0
	v_mov_b32_e32 v4, v0
	v_mov_b32_e32 v5, v0
	v_mov_b32_e32 v6, v0
	v_mov_b32_e32 v7, v0
	v_mov_b32_e32 v12, v0
	v_mov_b32_e32 v13, v0
	v_mov_b32_e32 v14, v0
	v_mov_b32_e32 v15, v0
	v_mov_b32_e32 v20, v0
	v_mov_b32_e32 v21, v0
	v_mov_b32_e32 v22, v0
	v_mov_b32_e32 v23, v0
	v_mov_b32_e32 v28, v0
	v_mov_b32_e32 v29, v0
	v_mov_b32_e32 v30, v0
	v_mov_b32_e32 v31, v0
	v_mov_b32_e32 v36, v0
	v_mov_b32_e32 v37, v0
	v_mov_b32_e32 v38, v0
	v_mov_b32_e32 v39, v0
	v_mov_b32_e32 v44, v0
	v_mov_b32_e32 v45, v0
	v_mov_b32_e32 v46, v0
	v_mov_b32_e32 v47, v0
	v_mov_b32_e32 v52, v0
	v_mov_b32_e32 v53, v0
	v_mov_b32_e32 v54, v0
	v_mov_b32_e32 v55, v0
	v_mov_b32_e32 v8, v0
	v_mov_b32_e32 v9, v0
	v_mov_b32_e32 v10, v0
	v_mov_b32_e32 v11, v0
	v_mov_b32_e32 v16, v0
	v_mov_b32_e32 v17, v0
	v_mov_b32_e32 v18, v0
	v_mov_b32_e32 v19, v0
	v_mov_b32_e32 v24, v0
	v_mov_b32_e32 v25, v0
	v_mov_b32_e32 v26, v0
	v_mov_b32_e32 v27, v0
	v_mov_b32_e32 v32, v0
	v_mov_b32_e32 v33, v0
	v_mov_b32_e32 v34, v0
	v_mov_b32_e32 v35, v0
	v_mov_b32_e32 v40, v0
	v_mov_b32_e32 v41, v0
	v_mov_b32_e32 v42, v0
	v_mov_b32_e32 v43, v0
	v_mov_b32_e32 v48, v0
	v_mov_b32_e32 v49, v0
	v_mov_b32_e32 v50, v0
	v_mov_b32_e32 v51, v0
	v_mov_b32_e32 v56, v0
	v_mov_b32_e32 v57, v0
	v_mov_b32_e32 v58, v0
	v_mov_b32_e32 v59, v0
	v_mov_b32_e32 v60, v0
	v_mov_b32_e32 v61, v0
	v_mov_b32_e32 v62, v0
	v_mov_b32_e32 v63, v0
	v_mov_b32_e32 v64, v0
	v_mov_b32_e32 v65, v0
	v_mov_b32_e32 v66, v0
	v_mov_b32_e32 v67, v0
	v_mov_b32_e32 v68, v0
	v_mov_b32_e32 v69, v0
	v_mov_b32_e32 v70, v0
	v_mov_b32_e32 v71, v0
	v_mov_b32_e32 v76, v0
	v_mov_b32_e32 v77, v0
	v_mov_b32_e32 v78, v0
	v_mov_b32_e32 v79, v0
	v_mov_b32_e32 v84, v0
	v_mov_b32_e32 v85, v0
	v_mov_b32_e32 v86, v0
	v_mov_b32_e32 v87, v0
	v_mov_b32_e32 v92, v0
	v_mov_b32_e32 v93, v0
	v_mov_b32_e32 v94, v0
	v_mov_b32_e32 v95, v0
	v_mov_b32_e32 v100, v0
	v_mov_b32_e32 v101, v0
	v_mov_b32_e32 v102, v0
	v_mov_b32_e32 v103, v0
	v_mov_b32_e32 v108, v0
	v_mov_b32_e32 v109, v0
	v_mov_b32_e32 v110, v0
	v_mov_b32_e32 v111, v0
	v_mov_b32_e32 v116, v0
	v_mov_b32_e32 v117, v0
	v_mov_b32_e32 v118, v0
	v_mov_b32_e32 v119, v0
	v_mov_b32_e32 v72, v0
	v_mov_b32_e32 v73, v0
	v_mov_b32_e32 v74, v0
	v_mov_b32_e32 v75, v0
	v_mov_b32_e32 v80, v0
	v_mov_b32_e32 v81, v0
	v_mov_b32_e32 v82, v0
	v_mov_b32_e32 v83, v0
	v_mov_b32_e32 v88, v0
	v_mov_b32_e32 v89, v0
	v_mov_b32_e32 v90, v0
	v_mov_b32_e32 v91, v0
	v_mov_b32_e32 v96, v0
	v_mov_b32_e32 v97, v0
	v_mov_b32_e32 v98, v0
	v_mov_b32_e32 v99, v0
	v_mov_b32_e32 v104, v0
	v_mov_b32_e32 v105, v0
	v_mov_b32_e32 v106, v0
	v_mov_b32_e32 v107, v0
	v_mov_b32_e32 v112, v0
	v_mov_b32_e32 v113, v0
	v_mov_b32_e32 v114, v0
	v_mov_b32_e32 v115, v0
	v_mov_b32_e32 v120, v0
	v_mov_b32_e32 v121, v0
	v_mov_b32_e32 v122, v0
	v_mov_b32_e32 v123, v0
	v_mov_b32_e32 v124, v0
	v_mov_b32_e32 v125, v0
	v_mov_b32_e32 v126, v0
	v_mov_b32_e32 v127, v0
	v_readfirstlane_b32 s98, v181
	s_lshr_b32 s98, s98, 8
	s_cmp_eq_u32 s98, 0
	s_cbranch_scc1 .LprioK2
	s_setprio 1
.LprioK2:
.LBB0_704:
	ds_read_b128 v[144:147], v156
	ds_read_b128 v[148:151], v156 offset:1024
	ds_read_b128 v[160:163], v156 offset:2048
	ds_read_b128 v[164:167], v156 offset:3072
	ds_read_b128 v[168:171], v157
	ds_read_b128 v[172:175], v157 offset:1024
	ds_read_b128 v[176:179], v157 offset:2048
	ds_read_b128 v[182:185], v157 offset:3072
	s_add_u32 s38, s36, 0xfff80080
	s_addc_u32 s39, s37, -1
	s_cmp_eq_u32 s57, 28
	s_cselect_b32 s41, s9, s39
	s_cselect_b32 s40, s27, s38
	s_cselect_b32 s39, s25, s56
	s_cselect_b32 s38, s35, s55
	v_lshl_add_u64 v[218:219], s[36:37], 0, v[136:137]
	s_add_i32 m0, s42, 0xc000
	ds_read_b128 v[186:189], v158
	ds_read_b128 v[190:193], v158 offset:1024
	ds_read_b128 v[194:197], v158 offset:2048
	ds_read_b128 v[198:201], v158 offset:3072
	ds_read_b128 v[202:205], v158 offset:4096
	ds_read_b128 v[206:209], v158 offset:5120
	ds_read_b128 v[210:213], v158 offset:6144
	ds_read_b128 v[214:217], v158 offset:7168
	global_load_lds_dwordx4 v[218:219], off
	v_lshl_add_u64 v[218:219], s[36:37], 0, v[138:139]
	s_add_i32 m0, s42, 0xe000
	s_nop 0
	global_load_lds_dwordx4 v[218:219], off
	s_waitcnt vmcnt(8)
	s_waitcnt lgkmcnt(0)
	s_barrier
; #define PG8_STAGE(bufoff, gbase, voff) do { _Pragma("unroll") for (int _i = 0; _i < 2; ++_i) \
;         __builtin_amdgcn_global_load_lds((const unsigned*)((const char*)(gbase) + (voff)[_i]), (LAS unsigned*)(lds + (bufoff) + ldsw + _i * 8192), 16, 0, 0); } while (0)
; #define PG8_LDA(dst, b, h) do { _Pragma("unroll") for (int m = 0; m < 4; ++m) _Pragma("unroll") for (int k = 0; k < 2; ++k) dst[m][k] = *(const LAS bf16x8*)(lds + PG8_SA(b, h) + aoff + m * 2048 + k * 1024); } while (0)
; #define PG8_MMA(ai, bj, At, Bt) do { __builtin_amdgcn_s_setprio(1); _Pragma("unroll") for (int m = 0; m < 4; ++m) _Pragma("unroll") for (int n = 0; n < 2; ++n) _Pragma("unroll") for (int k = 0; k < 2; ++k) \
;         acc[ai][bj][m][n] = __builtin_amdgcn_mfma_f32_16x16x32_bf16(Bt[n][k], At[m][k], acc[ai][bj][m][n], 0, 0, 0); __builtin_amdgcn_s_setprio(0); } while (0)
; #define PG8_WAIT_V(n) asm volatile("s_waitcnt vmcnt(" #n ")" ::: "memory")
; #define PG8_WAIT_L(n) asm volatile("s_waitcnt lgkmcnt(" #n ")" ::: "memory")
; #define PG8_BAR __builtin_amdgcn_s_barrier()
; #define PG8_SCHED __builtin_amdgcn_sched_barrier(0)
; template <class Epi, class Sched, bool ALIGN_EPI = true>
; __device__ __forceinline__ void gemm_phase(LAS unsigned char* lds, const Gemm g, const Sched& S, const Epi& E) {
;     ...
;             PG8_WAIT_V(8); PG8_WAIT_L(0); PG8_BAR; PG8_MMA(0, 0, At, B0); PG8_MMA(0, 1, At, B1); PG8_BAR; PG8_SCHED;
;             PG8_LDA(At, 0, 1); PG8_STAGE(PG8_SB(0, 0), b2, voffB); PG8_STAGE(PG8_SB(0, 1), b2 + hsB, voffB); PG8_STAGE(PG8_SA(0, 0), a2, voffA);
;             PG8_WAIT_V(8); PG8_WAIT_L(0); PG8_BAR; PG8_MMA(1, 0, At, B0); PG8_MMA(1, 1, At, B1); PG8_BAR; PG8_SCHED;
	s_waitcnt lgkmcnt(0)
	v_mfma_f32_16x16x32_bf16 v[124:127], v[144:147], v[186:189], v[124:127]
	v_mfma_f32_16x16x32_bf16 v[120:123], v[160:163], v[186:189], v[120:123]
	v_mfma_f32_16x16x32_bf16 v[112:115], v[144:147], v[194:197], v[112:115]
	v_mfma_f32_16x16x32_bf16 v[104:107], v[160:163], v[194:197], v[104:107]
	v_mfma_f32_16x16x32_bf16 v[96:99], v[144:147], v[202:205], v[96:99]
	v_mfma_f32_16x16x32_bf16 v[88:91], v[160:163], v[202:205], v[88:91]
	v_mfma_f32_16x16x32_bf16 v[80:83], v[144:147], v[210:213], v[80:83]
	v_mfma_f32_16x16x32_bf16 v[72:75], v[160:163], v[210:213], v[72:75]
	v_mfma_f32_16x16x32_bf16 v[124:127], v[148:151], v[190:193], v[124:127]
	v_mfma_f32_16x16x32_bf16 v[120:123], v[164:167], v[190:193], v[120:123]
	v_mfma_f32_16x16x32_bf16 v[112:115], v[148:151], v[198:201], v[112:115]
	v_mfma_f32_16x16x32_bf16 v[104:107], v[164:167], v[198:201], v[104:107]
	v_mfma_f32_16x16x32_bf16 v[96:99], v[148:151], v[206:209], v[96:99]
	v_mfma_f32_16x16x32_bf16 v[88:91], v[164:167], v[206:209], v[88:91]
	v_mfma_f32_16x16x32_bf16 v[80:83], v[148:151], v[214:217], v[80:83]
	v_mfma_f32_16x16x32_bf16 v[72:75], v[164:167], v[214:217], v[72:75]
	v_mfma_f32_16x16x32_bf16 v[116:119], v[168:171], v[186:189], v[116:119]
	v_mfma_f32_16x16x32_bf16 v[108:111], v[176:179], v[186:189], v[108:111]
	v_mfma_f32_16x16x32_bf16 v[100:103], v[168:171], v[194:197], v[100:103]
	v_mfma_f32_16x16x32_bf16 v[92:95], v[176:179], v[194:197], v[92:95]
	v_mfma_f32_16x16x32_bf16 v[84:87], v[168:171], v[202:205], v[84:87]
	v_mfma_f32_16x16x32_bf16 v[76:79], v[176:179], v[202:205], v[76:79]
	v_mfma_f32_16x16x32_bf16 v[68:71], v[168:171], v[210:213], v[68:71]
	v_mfma_f32_16x16x32_bf16 v[64:67], v[176:179], v[210:213], v[64:67]
	v_mfma_f32_16x16x32_bf16 v[116:119], v[172:175], v[190:193], v[116:119]
	v_mfma_f32_16x16x32_bf16 v[108:111], v[182:185], v[190:193], v[108:111]
	v_mfma_f32_16x16x32_bf16 v[100:103], v[172:175], v[198:201], v[100:103]
	v_mfma_f32_16x16x32_bf16 v[92:95], v[182:185], v[198:201], v[92:95]
	v_mfma_f32_16x16x32_bf16 v[84:87], v[172:175], v[206:209], v[84:87]
	v_mfma_f32_16x16x32_bf16 v[76:79], v[182:185], v[206:209], v[76:79]
	v_mfma_f32_16x16x32_bf16 v[68:71], v[172:175], v[214:217], v[68:71]
	v_mfma_f32_16x16x32_bf16 v[64:67], v[182:185], v[214:217], v[64:67]
	s_barrier
	s_add_i32 s58, s53, s33
	v_lshl_add_u64 v[218:219], s[38:39], 0, v[130:131]
	s_mov_b32 m0, s58
	ds_read_b128 v[186:189], v158 offset:16384
	ds_read_b128 v[190:193], v158 offset:17408
	ds_read_b128 v[194:197], v158 offset:18432
	ds_read_b128 v[198:201], v158 offset:19456
	ds_read_b128 v[202:205], v158 offset:20480
	ds_read_b128 v[206:209], v158 offset:21504
	ds_read_b128 v[210:213], v158 offset:22528
	ds_read_b128 v[214:217], v158 offset:23552
	global_load_lds_dwordx4 v[218:219], off
	s_add_i32 m0, s58, 0x2000
	s_add_u32 s58, s38, 0x80000
	v_lshl_add_u64 v[220:221], s[38:39], 0, v[134:135]
	s_addc_u32 s59, s39, 0
	s_add_i32 s60, s54, s33
	global_load_lds_dwordx4 v[220:221], off
	v_lshl_add_u64 v[222:223], s[58:59], 0, v[130:131]
	s_mov_b32 m0, s60
	v_lshl_add_u64 v[224:225], s[40:41], 0, v[132:133]
	global_load_lds_dwordx4 v[222:223], off
	v_lshl_add_u64 v[222:223], s[58:59], 0, v[134:135]
	s_add_i32 m0, s60, 0x2000
	s_nop 0
	global_load_lds_dwordx4 v[222:223], off
	v_lshl_add_u64 v[222:223], s[40:41], 0, v[128:129]
	s_mov_b32 m0, s42
	s_nop 0
	global_load_lds_dwordx4 v[222:223], off
	s_mov_b32 m0, s43
	s_nop 0
	global_load_lds_dwordx4 v[224:225], off
	s_waitcnt vmcnt(8)
	s_waitcnt lgkmcnt(0)
	s_barrier
	s_waitcnt lgkmcnt(0)
	v_mfma_f32_16x16x32_bf16 v[60:63], v[144:147], v[186:189], v[60:63]
	v_mfma_f32_16x16x32_bf16 v[56:59], v[160:163], v[186:189], v[56:59]
	v_mfma_f32_16x16x32_bf16 v[48:51], v[144:147], v[194:197], v[48:51]
	v_mfma_f32_16x16x32_bf16 v[40:43], v[160:163], v[194:197], v[40:43]
	v_mfma_f32_16x16x32_bf16 v[32:35], v[144:147], v[202:205], v[32:35]
	v_mfma_f32_16x16x32_bf16 v[24:27], v[160:163], v[202:205], v[24:27]
	v_mfma_f32_16x16x32_bf16 v[16:19], v[144:147], v[210:213], v[16:19]
	v_mfma_f32_16x16x32_bf16 v[8:11], v[160:163], v[210:213], v[8:11]
	v_mfma_f32_16x16x32_bf16 v[60:63], v[148:151], v[190:193], v[60:63]
	v_mfma_f32_16x16x32_bf16 v[56:59], v[164:167], v[190:193], v[56:59]
	v_mfma_f32_16x16x32_bf16 v[48:51], v[148:151], v[198:201], v[48:51]
	v_mfma_f32_16x16x32_bf16 v[40:43], v[164:167], v[198:201], v[40:43]
	v_mfma_f32_16x16x32_bf16 v[32:35], v[148:151], v[206:209], v[32:35]
	v_mfma_f32_16x16x32_bf16 v[24:27], v[164:167], v[206:209], v[24:27]
	v_mfma_f32_16x16x32_bf16 v[16:19], v[148:151], v[214:217], v[16:19]
	v_mfma_f32_16x16x32_bf16 v[8:11], v[164:167], v[214:217], v[8:11]
	v_mfma_f32_16x16x32_bf16 v[52:55], v[168:171], v[186:189], v[52:55]
	v_mfma_f32_16x16x32_bf16 v[44:47], v[176:179], v[186:189], v[44:47]
	v_mfma_f32_16x16x32_bf16 v[36:39], v[168:171], v[194:197], v[36:39]
	v_mfma_f32_16x16x32_bf16 v[28:31], v[176:179], v[194:197], v[28:31]
	v_mfma_f32_16x16x32_bf16 v[20:23], v[168:171], v[202:205], v[20:23]
	v_mfma_f32_16x16x32_bf16 v[12:15], v[176:179], v[202:205], v[12:15]
	v_mfma_f32_16x16x32_bf16 v[4:7], v[168:171], v[210:213], v[4:7]
	v_mfma_f32_16x16x32_bf16 v[0:3], v[176:179], v[210:213], v[0:3]
	v_mfma_f32_16x16x32_bf16 v[52:55], v[172:175], v[190:193], v[52:55]
	v_mfma_f32_16x16x32_bf16 v[44:47], v[182:185], v[190:193], v[44:47]
	v_mfma_f32_16x16x32_bf16 v[36:39], v[172:175], v[198:201], v[36:39]
	v_mfma_f32_16x16x32_bf16 v[28:31], v[182:185], v[198:201], v[28:31]
	v_mfma_f32_16x16x32_bf16 v[20:23], v[172:175], v[206:209], v[20:23]
	v_mfma_f32_16x16x32_bf16 v[12:15], v[182:185], v[206:209], v[12:15]
	v_mfma_f32_16x16x32_bf16 v[4:7], v[172:175], v[214:217], v[4:7]
	v_mfma_f32_16x16x32_bf16 v[0:3], v[182:185], v[214:217], v[0:3]
	s_barrier
; #define PG8_STAGE(bufoff, gbase, voff) do { _Pragma("unroll") for (int _i = 0; _i < 2; ++_i) \
;         __builtin_amdgcn_global_load_lds((const unsigned*)((const char*)(gbase) + (voff)[_i]), (LAS unsigned*)(lds + (bufoff) + ldsw + _i * 8192), 16, 0, 0); } while (0)
; #define PG8_LDA(dst, b, h) do { _Pragma("unroll") for (int m = 0; m < 4; ++m) _Pragma("unroll") for (int k = 0; k < 2; ++k) dst[m][k] = *(const LAS bf16x8*)(lds + PG8_SA(b, h) + aoff + m * 2048 + k * 1024); } while (0)
; #define PG8_LDB(dst, b, h) do { _Pragma("unroll") for (int n = 0; n < 2; ++n) _Pragma("unroll") for (int k = 0; k < 2; ++k) dst[n][k] = *(const LAS bf16x8*)(lds + PG8_SB(b, h) + boff + n * 2048 + k * 1024); } while (0)
; #define PG8_MMA(ai, bj, At, Bt) do { __builtin_amdgcn_s_setprio(1); _Pragma("unroll") for (int m = 0; m < 4; ++m) _Pragma("unroll") for (int n = 0; n < 2; ++n) _Pragma("unroll") for (int k = 0; k < 2; ++k) \
;         acc[ai][bj][m][n] = __builtin_amdgcn_mfma_f32_16x16x32_bf16(Bt[n][k], At[m][k], acc[ai][bj][m][n], 0, 0, 0); __builtin_amdgcn_s_setprio(0); } while (0)
; #define PG8_WAIT_V(n) asm volatile("s_waitcnt vmcnt(" #n ")" ::: "memory")
; #define PG8_WAIT_L(n) asm volatile("s_waitcnt lgkmcnt(" #n ")" ::: "memory")
; #define PG8_BAR __builtin_amdgcn_s_barrier()
; #define PG8_SCHED __builtin_amdgcn_sched_barrier(0)
; template <class Epi, class Sched, bool ALIGN_EPI = true>
; __device__ __forceinline__ void gemm_phase(LAS unsigned char* lds, const Gemm g, const Sched& S, const Epi& E) {
;     ...
;             PG8_LDB(B0, 1, 0); PG8_LDB(B1, 1, 1); PG8_SCHED; PG8_LDA(At, 1, 0); PG8_STAGE(PG8_SA(0, 1), a2 + hsA, voffA);
;             PG8_WAIT_V(8); PG8_WAIT_L(0); PG8_BAR; PG8_MMA(0, 0, At, B0); PG8_MMA(0, 1, At, B1); PG8_BAR; PG8_SCHED;
	s_add_i32 s58, 0, 0x18000
	v_add_u32_e32 v159, s58, v154
	s_add_i32 s59, 0, 0x1c000
	ds_read_b128 v[144:147], v159
	ds_read_b128 v[148:151], v159 offset:1024
	ds_read_b128 v[160:163], v159 offset:2048
	ds_read_b128 v[164:167], v159 offset:3072
	v_add_u32_e32 v159, s59, v154
	ds_read_b128 v[168:171], v159
	ds_read_b128 v[172:175], v159 offset:1024
	ds_read_b128 v[176:179], v159 offset:2048
	ds_read_b128 v[182:185], v159 offset:3072
	s_add_u32 s40, s40, 0x80000
	s_addc_u32 s41, s41, 0
	s_mov_b32 m0, s44
	v_lshl_add_u64 v[226:227], s[40:41], 0, v[128:129]
	ds_read_b128 v[186:189], v158 offset:32768
	ds_read_b128 v[190:193], v158 offset:33792
	ds_read_b128 v[194:197], v158 offset:34816
	ds_read_b128 v[198:201], v158 offset:35840
	ds_read_b128 v[202:205], v158 offset:36864
	ds_read_b128 v[206:209], v158 offset:37888
	ds_read_b128 v[210:213], v158 offset:38912
	ds_read_b128 v[214:217], v158 offset:39936
	global_load_lds_dwordx4 v[226:227], off
	v_lshl_add_u64 v[226:227], s[40:41], 0, v[132:133]
	s_mov_b32 m0, s45
	s_nop 0
	global_load_lds_dwordx4 v[226:227], off
	s_waitcnt vmcnt(8)
	s_waitcnt lgkmcnt(0)
	s_barrier
	s_waitcnt lgkmcnt(0)
	v_mfma_f32_16x16x32_bf16 v[124:127], v[144:147], v[186:189], v[124:127]
	v_mfma_f32_16x16x32_bf16 v[120:123], v[160:163], v[186:189], v[120:123]
	v_mfma_f32_16x16x32_bf16 v[112:115], v[144:147], v[194:197], v[112:115]
	v_mfma_f32_16x16x32_bf16 v[104:107], v[160:163], v[194:197], v[104:107]
	v_mfma_f32_16x16x32_bf16 v[96:99], v[144:147], v[202:205], v[96:99]
	v_mfma_f32_16x16x32_bf16 v[88:91], v[160:163], v[202:205], v[88:91]
	v_mfma_f32_16x16x32_bf16 v[80:83], v[144:147], v[210:213], v[80:83]
	v_mfma_f32_16x16x32_bf16 v[72:75], v[160:163], v[210:213], v[72:75]
	v_mfma_f32_16x16x32_bf16 v[124:127], v[148:151], v[190:193], v[124:127]
	v_mfma_f32_16x16x32_bf16 v[120:123], v[164:167], v[190:193], v[120:123]
	v_mfma_f32_16x16x32_bf16 v[112:115], v[148:151], v[198:201], v[112:115]
	v_mfma_f32_16x16x32_bf16 v[104:107], v[164:167], v[198:201], v[104:107]
	v_mfma_f32_16x16x32_bf16 v[96:99], v[148:151], v[206:209], v[96:99]
	v_mfma_f32_16x16x32_bf16 v[88:91], v[164:167], v[206:209], v[88:91]
	v_mfma_f32_16x16x32_bf16 v[80:83], v[148:151], v[214:217], v[80:83]
	v_mfma_f32_16x16x32_bf16 v[72:75], v[164:167], v[214:217], v[72:75]
	v_mfma_f32_16x16x32_bf16 v[116:119], v[168:171], v[186:189], v[116:119]
	v_mfma_f32_16x16x32_bf16 v[108:111], v[176:179], v[186:189], v[108:111]
	v_mfma_f32_16x16x32_bf16 v[100:103], v[168:171], v[194:197], v[100:103]
	v_mfma_f32_16x16x32_bf16 v[92:95], v[176:179], v[194:197], v[92:95]
	v_mfma_f32_16x16x32_bf16 v[84:87], v[168:171], v[202:205], v[84:87]
	v_mfma_f32_16x16x32_bf16 v[76:79], v[176:179], v[202:205], v[76:79]
	v_mfma_f32_16x16x32_bf16 v[68:71], v[168:171], v[210:213], v[68:71]
	v_mfma_f32_16x16x32_bf16 v[64:67], v[176:179], v[210:213], v[64:67]
	v_mfma_f32_16x16x32_bf16 v[116:119], v[172:175], v[190:193], v[116:119]
	v_mfma_f32_16x16x32_bf16 v[108:111], v[182:185], v[190:193], v[108:111]
	v_mfma_f32_16x16x32_bf16 v[100:103], v[172:175], v[198:201], v[100:103]
	v_mfma_f32_16x16x32_bf16 v[92:95], v[182:185], v[198:201], v[92:95]
	v_mfma_f32_16x16x32_bf16 v[84:87], v[172:175], v[206:209], v[84:87]
	v_mfma_f32_16x16x32_bf16 v[76:79], v[182:185], v[206:209], v[76:79]
	v_mfma_f32_16x16x32_bf16 v[68:71], v[172:175], v[214:217], v[68:71]
	v_mfma_f32_16x16x32_bf16 v[64:67], v[182:185], v[214:217], v[64:67]
	s_barrier
; #define PG8_STAGE(bufoff, gbase, voff) do { _Pragma("unroll") for (int _i = 0; _i < 2; ++_i) \
;         __builtin_amdgcn_global_load_lds((const unsigned*)((const char*)(gbase) + (voff)[_i]), (LAS unsigned*)(lds + (bufoff) + ldsw + _i * 8192), 16, 0, 0); } while (0)
; #define PG8_LDA(dst, b, h) do { _Pragma("unroll") for (int m = 0; m < 4; ++m) _Pragma("unroll") for (int k = 0; k < 2; ++k) dst[m][k] = *(const LAS bf16x8*)(lds + PG8_SA(b, h) + aoff + m * 2048 + k * 1024); } while (0)
; #define PG8_MMA(ai, bj, At, Bt) do { __builtin_amdgcn_s_setprio(1); _Pragma("unroll") for (int m = 0; m < 4; ++m) _Pragma("unroll") for (int n = 0; n < 2; ++n) _Pragma("unroll") for (int k = 0; k < 2; ++k) \
;         acc[ai][bj][m][n] = __builtin_amdgcn_mfma_f32_16x16x32_bf16(Bt[n][k], At[m][k], acc[ai][bj][m][n], 0, 0, 0); __builtin_amdgcn_s_setprio(0); } while (0)
; #define PG8_WAIT_V(n) asm volatile("s_waitcnt vmcnt(" #n ")" ::: "memory")
; #define PG8_WAIT_L(n) asm volatile("s_waitcnt lgkmcnt(" #n ")" ::: "memory")
; #define PG8_BAR __builtin_amdgcn_s_barrier()
; #define PG8_SCHED __builtin_amdgcn_sched_barrier(0)
; template <class Epi, class Sched, bool ALIGN_EPI = true>
; __device__ __forceinline__ void gemm_phase(LAS unsigned char* lds, const Gemm g, const Sched& S, const Epi& E) {
;     ...
;             PG8_LDA(At, 1, 1); PG8_STAGE(PG8_SB(1, 0), b3, voffB); PG8_STAGE(PG8_SB(1, 1), b3 + hsB, voffB); PG8_STAGE(PG8_SA(1, 0), a3, voffA);
;             PG8_WAIT_V(8); PG8_WAIT_L(0); PG8_BAR; PG8_MMA(1, 0, At, B0); PG8_MMA(1, 1, At, B1); PG8_BAR; PG8_SCHED;
;         }
;         if constexpr (ALIGN_EPI) { if (wr == 0) PG8_BAR; }
	s_add_i32 s40, s58, s33
	v_lshl_add_u64 v[218:219], v[218:219], 0, s[12:13]
	s_mov_b32 m0, s40
	ds_read_b128 v[186:189], v158 offset:49152
	ds_read_b128 v[190:193], v158 offset:50176
	ds_read_b128 v[194:197], v158 offset:51200
	ds_read_b128 v[198:201], v158 offset:52224
	ds_read_b128 v[202:205], v158 offset:53248
	ds_read_b128 v[206:209], v158 offset:54272
	ds_read_b128 v[210:213], v158 offset:55296
	ds_read_b128 v[214:217], v158 offset:56320
	global_load_lds_dwordx4 v[218:219], off
	s_add_i32 m0, s40, 0x2000
	s_add_u32 s38, s38, 0x80080
	v_lshl_add_u64 v[218:219], v[220:221], 0, s[12:13]
	s_addc_u32 s39, s39, 0
	s_add_i32 s40, s59, s33
	global_load_lds_dwordx4 v[218:219], off
	v_lshl_add_u64 v[218:219], s[38:39], 0, v[130:131]
	s_mov_b32 m0, s40
	s_nop 0
	global_load_lds_dwordx4 v[218:219], off
	v_lshl_add_u64 v[218:219], s[38:39], 0, v[134:135]
	s_add_i32 m0, s40, 0x2000
	s_nop 0
	global_load_lds_dwordx4 v[218:219], off
	v_lshl_add_u64 v[218:219], v[222:223], 0, s[12:13]
	s_mov_b32 m0, s48
	s_nop 0
	global_load_lds_dwordx4 v[218:219], off
	v_lshl_add_u64 v[218:219], v[224:225], 0, s[12:13]
	s_mov_b32 m0, s49
	s_nop 0
	global_load_lds_dwordx4 v[218:219], off
	s_waitcnt vmcnt(8)
	s_waitcnt lgkmcnt(0)
	s_barrier
	s_waitcnt lgkmcnt(0)
	v_mfma_f32_16x16x32_bf16 v[60:63], v[144:147], v[186:189], v[60:63]
	v_mfma_f32_16x16x32_bf16 v[56:59], v[160:163], v[186:189], v[56:59]
	v_mfma_f32_16x16x32_bf16 v[48:51], v[144:147], v[194:197], v[48:51]
	v_mfma_f32_16x16x32_bf16 v[40:43], v[160:163], v[194:197], v[40:43]
	v_mfma_f32_16x16x32_bf16 v[32:35], v[144:147], v[202:205], v[32:35]
	v_mfma_f32_16x16x32_bf16 v[24:27], v[160:163], v[202:205], v[24:27]
	v_mfma_f32_16x16x32_bf16 v[16:19], v[144:147], v[210:213], v[16:19]
	v_mfma_f32_16x16x32_bf16 v[8:11], v[160:163], v[210:213], v[8:11]
	v_mfma_f32_16x16x32_bf16 v[60:63], v[148:151], v[190:193], v[60:63]
	v_mfma_f32_16x16x32_bf16 v[56:59], v[164:167], v[190:193], v[56:59]
	v_mfma_f32_16x16x32_bf16 v[48:51], v[148:151], v[198:201], v[48:51]
	v_mfma_f32_16x16x32_bf16 v[40:43], v[164:167], v[198:201], v[40:43]
	v_mfma_f32_16x16x32_bf16 v[32:35], v[148:151], v[206:209], v[32:35]
	v_mfma_f32_16x16x32_bf16 v[24:27], v[164:167], v[206:209], v[24:27]
	v_mfma_f32_16x16x32_bf16 v[16:19], v[148:151], v[214:217], v[16:19]
	v_mfma_f32_16x16x32_bf16 v[8:11], v[164:167], v[214:217], v[8:11]
	v_mfma_f32_16x16x32_bf16 v[52:55], v[168:171], v[186:189], v[52:55]
	v_mfma_f32_16x16x32_bf16 v[44:47], v[176:179], v[186:189], v[44:47]
	v_mfma_f32_16x16x32_bf16 v[36:39], v[168:171], v[194:197], v[36:39]
	v_mfma_f32_16x16x32_bf16 v[28:31], v[176:179], v[194:197], v[28:31]
	v_mfma_f32_16x16x32_bf16 v[20:23], v[168:171], v[202:205], v[20:23]
	v_mfma_f32_16x16x32_bf16 v[12:15], v[176:179], v[202:205], v[12:15]
	v_mfma_f32_16x16x32_bf16 v[4:7], v[168:171], v[210:213], v[4:7]
	v_mfma_f32_16x16x32_bf16 v[0:3], v[176:179], v[210:213], v[0:3]
	v_mfma_f32_16x16x32_bf16 v[52:55], v[172:175], v[190:193], v[52:55]
	v_mfma_f32_16x16x32_bf16 v[44:47], v[182:185], v[190:193], v[44:47]
	v_mfma_f32_16x16x32_bf16 v[36:39], v[172:175], v[198:201], v[36:39]
	v_mfma_f32_16x16x32_bf16 v[28:31], v[182:185], v[198:201], v[28:31]
	v_mfma_f32_16x16x32_bf16 v[20:23], v[172:175], v[206:209], v[20:23]
	v_mfma_f32_16x16x32_bf16 v[12:15], v[182:185], v[206:209], v[12:15]
	v_mfma_f32_16x16x32_bf16 v[4:7], v[172:175], v[214:217], v[4:7]
	v_mfma_f32_16x16x32_bf16 v[0:3], v[182:185], v[214:217], v[0:3]
	s_barrier
	s_add_i32 s57, s57, 2
	s_add_u32 s36, s36, 0x100
	s_addc_u32 s37, s37, 0
	s_add_u32 s55, s55, 0x100
	s_addc_u32 s56, s56, 0
	s_cmp_gt_u32 s57, 29
	s_cbranch_scc0 .LBB0_704
	s_setprio 0
	s_and_b64 vcc, exec, s[14:15]
	s_cbranch_vccz .LBB0_707
	s_barrier

; #define PG8_STAGE(bufoff, gbase, voff) do { _Pragma("unroll") for (int _i = 0; _i < 2; ++_i) \
;         __builtin_amdgcn_global_load_lds((const unsigned*)((const char*)(gbase) + (voff)[_i]), (LAS unsigned*)(lds + (bufoff) + ldsw + _i * 8192), 16, 0, 0); } while (0)
; #define PG8_LDA(dst, b, h) do { _Pragma("unroll") for (int m = 0; m < 4; ++m) _Pragma("unroll") for (int k = 0; k < 2; ++k) dst[m][k] = *(const LAS bf16x8*)(lds + PG8_SA(b, h) + aoff + m * 2048 + k * 1024); } while (0)
; #define PG8_LDB(dst, b, h) do { _Pragma("unroll") for (int n = 0; n < 2; ++n) _Pragma("unroll") for (int k = 0; k < 2; ++k) dst[n][k] = *(const LAS bf16x8*)(lds + PG8_SB(b, h) + boff + n * 2048 + k * 1024); } while (0)
; #define PG8_MMA(ai, bj, At, Bt) do { __builtin_amdgcn_s_setprio(1); _Pragma("unroll") for (int m = 0; m < 4; ++m) _Pragma("unroll") for (int n = 0; n < 2; ++n) _Pragma("unroll") for (int k = 0; k < 2; ++k) \
;         acc[ai][bj][m][n] = __builtin_amdgcn_mfma_f32_16x16x32_bf16(Bt[n][k], At[m][k], acc[ai][bj][m][n], 0, 0, 0); __builtin_amdgcn_s_setprio(0); } while (0)
; template <class Epi, class Sched, bool ALIGN_EPI = true>
; __device__ __forceinline__ void gemm_phase(LAS unsigned char* lds, const Gemm g, const Sched& S, const Epi& E) {
;     ...
;         const bool has_next = S.next(ui + 1, nxt);
;         const char* nA = has_next ? (const char*)g.A + ((long)nxt.pm * g.mstride + g.moff) * (long)(g.lda * 2) : cA; const char* nB = has_next ? (const char*)g.Bt + (size_t)nxt.pn * tsB : cB;
;         for (int t = 0; t < nt; t += 2) {
;             const bool last = (t == nt - 2);
;             const char* a1 = cA + (size_t)(t + 1) * kstep;
;             const char* a2 = last ? nA : cA + (size_t)(t + 2) * kstep; const char* b2 = last ? nB : cB + (size_t)(t + 2) * kstep;
;             const char* a3 = a2 + kstep; const char* b3 = b2 + kstep;
;             PG8_LDB(B0, 0, 0); PG8_LDB(B1, 0, 1); PG8_SCHED; PG8_LDA(At, 0, 0); PG8_STAGE(PG8_SA(1, 1), a1 + hsA, voffA);
;             PG8_WAIT_V(8); PG8_WAIT_L(0); PG8_BAR; PG8_MMA(0, 0, At, B0); PG8_MMA(0, 1, At, B1); PG8_BAR; PG8_SCHED;
;     ...
;         for (int a = 0; a < 2; ++a)
; #pragma unroll
;             for (int b = 0; b < 2; ++b)
; #pragma unroll
;                 for (int m = 0; m < 4; ++m)
; #pragma unroll
;                     for (int n = 0; n < 2; ++n) acc[a][b][m][n] = (f32x4){0.f, 0.f, 0.f, 0.f};
.LBB0_880:
	s_ashr_i32 s21, s20, 31
	s_lshl_b64 s[24:25], s[20:21], 19
	s_add_u32 s24, s10, s24
	s_addc_u32 s25, s11, s25
	s_and_b64 s[6:7], s[6:7], exec
	s_cselect_b32 s9, s25, s27
	s_cselect_b32 s21, s24, s26
	s_add_u32 s6, s28, 0x40080
	s_addc_u32 s7, s29, 0
	s_add_u32 s31, s26, 0x100
	v_mov_b32_e32 v0, 0
	s_addc_u32 s34, s27, 0
	s_mov_b32 s35, -2
	v_mov_b32_e32 v1, v0
	v_mov_b32_e32 v2, v0
	v_mov_b32_e32 v3, v0
	s_waitcnt vmcnt(0)
	v_mov_b32_e32 v60, v0
	v_mov_b32_e32 v61, v0
	v_mov_b32_e32 v62, v0
	v_mov_b32_e32 v63, v0
	v_mov_b32_e32 v8, v0
	v_mov_b32_e32 v9, v0
	v_mov_b32_e32 v10, v0
	v_mov_b32_e32 v11, v0
	v_mov_b32_e32 v72, v0
	v_mov_b32_e32 v73, v0
	v_mov_b32_e32 v74, v0
	v_mov_b32_e32 v75, v0
	v_mov_b32_e32 v16, v0
	v_mov_b32_e32 v17, v0
	v_mov_b32_e32 v18, v0
	v_mov_b32_e32 v19, v0
	v_mov_b32_e32 v80, v0
	v_mov_b32_e32 v81, v0
	v_mov_b32_e32 v82, v0
	v_mov_b32_e32 v83, v0
	v_mov_b32_e32 v24, v0
	v_mov_b32_e32 v25, v0
	v_mov_b32_e32 v26, v0
	v_mov_b32_e32 v27, v0
	v_mov_b32_e32 v88, v0
	v_mov_b32_e32 v89, v0
	v_mov_b32_e32 v90, v0
	v_mov_b32_e32 v91, v0
	v_mov_b32_e32 v4, v0
	v_mov_b32_e32 v5, v0
	v_mov_b32_e32 v6, v0
	v_mov_b32_e32 v7, v0
	v_mov_b32_e32 v68, v0
	v_mov_b32_e32 v69, v0
	v_mov_b32_e32 v70, v0
	v_mov_b32_e32 v71, v0
	v_mov_b32_e32 v12, v0
	v_mov_b32_e32 v13, v0
	v_mov_b32_e32 v14, v0
	v_mov_b32_e32 v15, v0
	v_mov_b32_e32 v76, v0
	v_mov_b32_e32 v77, v0
	v_mov_b32_e32 v78, v0
	v_mov_b32_e32 v79, v0
	v_mov_b32_e32 v20, v0
	v_mov_b32_e32 v21, v0
	v_mov_b32_e32 v22, v0
	v_mov_b32_e32 v23, v0
	v_mov_b32_e32 v84, v0
	v_mov_b32_e32 v85, v0
	v_mov_b32_e32 v86, v0
	v_mov_b32_e32 v87, v0
	v_mov_b32_e32 v28, v0
	v_mov_b32_e32 v29, v0
	v_mov_b32_e32 v30, v0
	v_mov_b32_e32 v31, v0
	v_mov_b32_e32 v92, v0
	v_mov_b32_e32 v93, v0
	v_mov_b32_e32 v94, v0
	v_mov_b32_e32 v95, v0
	v_mov_b32_e32 v32, v0
	v_mov_b32_e32 v33, v0
	v_mov_b32_e32 v34, v0
	v_mov_b32_e32 v35, v0
	v_mov_b32_e32 v96, v0
	v_mov_b32_e32 v97, v0
	v_mov_b32_e32 v98, v0
	v_mov_b32_e32 v99, v0
	v_mov_b32_e32 v40, v0
	v_mov_b32_e32 v41, v0
	v_mov_b32_e32 v42, v0
	v_mov_b32_e32 v43, v0
	v_mov_b32_e32 v104, v0
	v_mov_b32_e32 v105, v0
	v_mov_b32_e32 v106, v0
	v_mov_b32_e32 v107, v0
	v_mov_b32_e32 v48, v0
	v_mov_b32_e32 v49, v0
	v_mov_b32_e32 v50, v0
	v_mov_b32_e32 v51, v0
	v_mov_b32_e32 v112, v0
	v_mov_b32_e32 v113, v0
	v_mov_b32_e32 v114, v0
	v_mov_b32_e32 v115, v0
	v_mov_b32_e32 v56, v0
	v_mov_b32_e32 v57, v0
	v_mov_b32_e32 v58, v0
	v_mov_b32_e32 v59, v0
	v_mov_b32_e32 v136, v0
	v_mov_b32_e32 v137, v0
	v_mov_b32_e32 v138, v0
	v_mov_b32_e32 v139, v0
	v_mov_b32_e32 v36, v0
	v_mov_b32_e32 v37, v0
	v_mov_b32_e32 v38, v0
	v_mov_b32_e32 v39, v0
	v_mov_b32_e32 v100, v0
	v_mov_b32_e32 v101, v0
	v_mov_b32_e32 v102, v0
	v_mov_b32_e32 v103, v0
	v_mov_b32_e32 v44, v0
	v_mov_b32_e32 v45, v0
	v_mov_b32_e32 v46, v0
	v_mov_b32_e32 v47, v0
	v_mov_b32_e32 v108, v0
	v_mov_b32_e32 v109, v0
	v_mov_b32_e32 v110, v0
	v_mov_b32_e32 v111, v0
	v_mov_b32_e32 v52, v0
	v_mov_b32_e32 v53, v0
	v_mov_b32_e32 v54, v0
	v_mov_b32_e32 v55, v0
	v_mov_b32_e32 v124, v0
	v_mov_b32_e32 v125, v0
	v_mov_b32_e32 v126, v0
	v_mov_b32_e32 v127, v0
	v_mov_b32_e32 v64, v0
	v_mov_b32_e32 v65, v0
	v_mov_b32_e32 v66, v0
	v_mov_b32_e32 v67, v0
	v_mov_b32_e32 v140, v0
	v_mov_b32_e32 v141, v0
	v_mov_b32_e32 v142, v0
	v_mov_b32_e32 v143, v0
	v_readfirstlane_b32 s98, v181
	s_lshr_b32 s98, s98, 8
	s_cmp_eq_u32 s98, 0
	s_cbranch_scc1 .LprioK3
	s_setprio 1
.LprioK3:
.LBB0_881:
	ds_read_b128 v[116:119], v184
	ds_read_b128 v[120:123], v184 offset:1024
	ds_read_b128 v[128:131], v184 offset:2048
	ds_read_b128 v[132:135], v184 offset:3072
	ds_read_b128 v[144:147], v185
	ds_read_b128 v[148:151], v185 offset:1024
	ds_read_b128 v[170:173], v185 offset:2048
	ds_read_b128 v[174:177], v185 offset:3072
	s_add_u32 s26, s6, 0xfffc0080
	s_addc_u32 s27, s7, -1
	s_cmp_eq_u32 s35, 12
	s_cselect_b32 s29, s23, s27
	s_cselect_b32 s28, s22, s26
	s_cselect_b32 s27, s9, s34
	s_cselect_b32 s26, s21, s31
	v_lshl_add_u64 v[178:179], s[6:7], 0, v[162:163]
	s_add_i32 m0, s42, 0xc000
	ds_read_b128 v[188:191], v186
	ds_read_b128 v[192:195], v186 offset:1024
	ds_read_b128 v[196:199], v186 offset:2048
	ds_read_b128 v[200:203], v186 offset:3072
	ds_read_b128 v[204:207], v186 offset:4096
	ds_read_b128 v[208:211], v186 offset:5120
	ds_read_b128 v[212:215], v186 offset:6144
	ds_read_b128 v[216:219], v186 offset:7168
	global_load_lds_dwordx4 v[178:179], off
	v_lshl_add_u64 v[178:179], s[6:7], 0, v[164:165]
	s_add_i32 m0, s42, 0xe000
	s_nop 0
	global_load_lds_dwordx4 v[178:179], off
	s_waitcnt vmcnt(8)
	s_waitcnt lgkmcnt(0)
	s_barrier
; #define PG8_STAGE(bufoff, gbase, voff) do { _Pragma("unroll") for (int _i = 0; _i < 2; ++_i) \
;         __builtin_amdgcn_global_load_lds((const unsigned*)((const char*)(gbase) + (voff)[_i]), (LAS unsigned*)(lds + (bufoff) + ldsw + _i * 8192), 16, 0, 0); } while (0)
; #define PG8_LDA(dst, b, h) do { _Pragma("unroll") for (int m = 0; m < 4; ++m) _Pragma("unroll") for (int k = 0; k < 2; ++k) dst[m][k] = *(const LAS bf16x8*)(lds + PG8_SA(b, h) + aoff + m * 2048 + k * 1024); } while (0)
; #define PG8_MMA(ai, bj, At, Bt) do { __builtin_amdgcn_s_setprio(1); _Pragma("unroll") for (int m = 0; m < 4; ++m) _Pragma("unroll") for (int n = 0; n < 2; ++n) _Pragma("unroll") for (int k = 0; k < 2; ++k) \
;         acc[ai][bj][m][n] = __builtin_amdgcn_mfma_f32_16x16x32_bf16(Bt[n][k], At[m][k], acc[ai][bj][m][n], 0, 0, 0); __builtin_amdgcn_s_setprio(0); } while (0)
; #define PG8_WAIT_V(n) asm volatile("s_waitcnt vmcnt(" #n ")" ::: "memory")
; #define PG8_WAIT_L(n) asm volatile("s_waitcnt lgkmcnt(" #n ")" ::: "memory")
; #define PG8_BAR __builtin_amdgcn_s_barrier()
; #define PG8_SCHED __builtin_amdgcn_sched_barrier(0)
; template <class Epi, class Sched, bool ALIGN_EPI = true>
; __device__ __forceinline__ void gemm_phase(LAS unsigned char* lds, const Gemm g, const Sched& S, const Epi& E) {
;     ...
;             PG8_WAIT_V(8); PG8_WAIT_L(0); PG8_BAR; PG8_MMA(0, 0, At, B0); PG8_MMA(0, 1, At, B1); PG8_BAR; PG8_SCHED;
;             PG8_LDA(At, 0, 1); PG8_STAGE(PG8_SB(0, 0), b2, voffB); PG8_STAGE(PG8_SB(0, 1), b2 + hsB, voffB); PG8_STAGE(PG8_SA(0, 0), a2, voffA);
;             PG8_WAIT_V(8); PG8_WAIT_L(0); PG8_BAR; PG8_MMA(1, 0, At, B0); PG8_MMA(1, 1, At, B1); PG8_BAR; PG8_SCHED;
	s_waitcnt lgkmcnt(0)
	v_mfma_f32_16x16x32_bf16 v[140:143], v[116:119], v[188:191], v[140:143]
	v_mfma_f32_16x16x32_bf16 v[64:67], v[128:131], v[188:191], v[64:67]
	v_mfma_f32_16x16x32_bf16 v[124:127], v[116:119], v[196:199], v[124:127]
	v_mfma_f32_16x16x32_bf16 v[52:55], v[128:131], v[196:199], v[52:55]
	v_mfma_f32_16x16x32_bf16 v[108:111], v[116:119], v[204:207], v[108:111]
	v_mfma_f32_16x16x32_bf16 v[44:47], v[128:131], v[204:207], v[44:47]
	v_mfma_f32_16x16x32_bf16 v[100:103], v[116:119], v[212:215], v[100:103]
	v_mfma_f32_16x16x32_bf16 v[36:39], v[128:131], v[212:215], v[36:39]
	v_mfma_f32_16x16x32_bf16 v[140:143], v[120:123], v[192:195], v[140:143]
	v_mfma_f32_16x16x32_bf16 v[64:67], v[132:135], v[192:195], v[64:67]
	v_mfma_f32_16x16x32_bf16 v[124:127], v[120:123], v[200:203], v[124:127]
	v_mfma_f32_16x16x32_bf16 v[52:55], v[132:135], v[200:203], v[52:55]
	v_mfma_f32_16x16x32_bf16 v[108:111], v[120:123], v[208:211], v[108:111]
	v_mfma_f32_16x16x32_bf16 v[44:47], v[132:135], v[208:211], v[44:47]
	v_mfma_f32_16x16x32_bf16 v[100:103], v[120:123], v[216:219], v[100:103]
	v_mfma_f32_16x16x32_bf16 v[36:39], v[132:135], v[216:219], v[36:39]
	v_mfma_f32_16x16x32_bf16 v[136:139], v[144:147], v[188:191], v[136:139]
	v_mfma_f32_16x16x32_bf16 v[56:59], v[170:173], v[188:191], v[56:59]
	v_mfma_f32_16x16x32_bf16 v[112:115], v[144:147], v[196:199], v[112:115]
	v_mfma_f32_16x16x32_bf16 v[48:51], v[170:173], v[196:199], v[48:51]
	v_mfma_f32_16x16x32_bf16 v[104:107], v[144:147], v[204:207], v[104:107]
	v_mfma_f32_16x16x32_bf16 v[40:43], v[170:173], v[204:207], v[40:43]
	v_mfma_f32_16x16x32_bf16 v[96:99], v[144:147], v[212:215], v[96:99]
	v_mfma_f32_16x16x32_bf16 v[32:35], v[170:173], v[212:215], v[32:35]
	v_mfma_f32_16x16x32_bf16 v[136:139], v[148:151], v[192:195], v[136:139]
	v_mfma_f32_16x16x32_bf16 v[56:59], v[174:177], v[192:195], v[56:59]
	v_mfma_f32_16x16x32_bf16 v[112:115], v[148:151], v[200:203], v[112:115]
	v_mfma_f32_16x16x32_bf16 v[48:51], v[174:177], v[200:203], v[48:51]
	v_mfma_f32_16x16x32_bf16 v[104:107], v[148:151], v[208:211], v[104:107]
	v_mfma_f32_16x16x32_bf16 v[40:43], v[174:177], v[208:211], v[40:43]
	v_mfma_f32_16x16x32_bf16 v[96:99], v[148:151], v[216:219], v[96:99]
	v_mfma_f32_16x16x32_bf16 v[32:35], v[174:177], v[216:219], v[32:35]
	s_barrier
	s_add_i32 s36, s62, s33
	v_lshl_add_u64 v[178:179], s[26:27], 0, v[156:157]
	s_mov_b32 m0, s36
	ds_read_b128 v[188:191], v186 offset:16384
	ds_read_b128 v[192:195], v186 offset:17408
	ds_read_b128 v[196:199], v186 offset:18432
	ds_read_b128 v[200:203], v186 offset:19456
	ds_read_b128 v[204:207], v186 offset:20480
	ds_read_b128 v[208:211], v186 offset:21504
	ds_read_b128 v[212:215], v186 offset:22528
	ds_read_b128 v[216:219], v186 offset:23552
	global_load_lds_dwordx4 v[178:179], off
	s_add_i32 m0, s36, 0x2000
	s_add_u32 s36, s26, 0x40000
	v_lshl_add_u64 v[220:221], s[26:27], 0, v[160:161]
	s_addc_u32 s37, s27, 0
	s_add_i32 s38, s63, s33
	global_load_lds_dwordx4 v[220:221], off
	v_lshl_add_u64 v[222:223], s[36:37], 0, v[156:157]
	s_mov_b32 m0, s38
	v_lshl_add_u64 v[224:225], s[28:29], 0, v[158:159]
	global_load_lds_dwordx4 v[222:223], off
	v_lshl_add_u64 v[222:223], s[36:37], 0, v[160:161]
	s_add_i32 m0, s38, 0x2000
	s_nop 0
	global_load_lds_dwordx4 v[222:223], off
	v_lshl_add_u64 v[222:223], s[28:29], 0, v[154:155]
	s_mov_b32 m0, s42
	s_nop 0
	global_load_lds_dwordx4 v[222:223], off
	s_mov_b32 m0, s43
	s_nop 0
	global_load_lds_dwordx4 v[224:225], off
	s_waitcnt vmcnt(8)
	s_waitcnt lgkmcnt(0)
	s_barrier
	s_waitcnt lgkmcnt(0)
	v_mfma_f32_16x16x32_bf16 v[92:95], v[116:119], v[188:191], v[92:95]
	v_mfma_f32_16x16x32_bf16 v[28:31], v[128:131], v[188:191], v[28:31]
	v_mfma_f32_16x16x32_bf16 v[84:87], v[116:119], v[196:199], v[84:87]
	v_mfma_f32_16x16x32_bf16 v[20:23], v[128:131], v[196:199], v[20:23]
	v_mfma_f32_16x16x32_bf16 v[76:79], v[116:119], v[204:207], v[76:79]
	v_mfma_f32_16x16x32_bf16 v[12:15], v[128:131], v[204:207], v[12:15]
	v_mfma_f32_16x16x32_bf16 v[68:71], v[116:119], v[212:215], v[68:71]
	v_mfma_f32_16x16x32_bf16 v[4:7], v[128:131], v[212:215], v[4:7]
	v_mfma_f32_16x16x32_bf16 v[92:95], v[120:123], v[192:195], v[92:95]
	v_mfma_f32_16x16x32_bf16 v[28:31], v[132:135], v[192:195], v[28:31]
	v_mfma_f32_16x16x32_bf16 v[84:87], v[120:123], v[200:203], v[84:87]
	v_mfma_f32_16x16x32_bf16 v[20:23], v[132:135], v[200:203], v[20:23]
	v_mfma_f32_16x16x32_bf16 v[76:79], v[120:123], v[208:211], v[76:79]
	v_mfma_f32_16x16x32_bf16 v[12:15], v[132:135], v[208:211], v[12:15]
	v_mfma_f32_16x16x32_bf16 v[68:71], v[120:123], v[216:219], v[68:71]
	v_mfma_f32_16x16x32_bf16 v[4:7], v[132:135], v[216:219], v[4:7]
	v_mfma_f32_16x16x32_bf16 v[88:91], v[144:147], v[188:191], v[88:91]
	v_mfma_f32_16x16x32_bf16 v[24:27], v[170:173], v[188:191], v[24:27]
	v_mfma_f32_16x16x32_bf16 v[80:83], v[144:147], v[196:199], v[80:83]
	v_mfma_f32_16x16x32_bf16 v[16:19], v[170:173], v[196:199], v[16:19]
	v_mfma_f32_16x16x32_bf16 v[72:75], v[144:147], v[204:207], v[72:75]
	v_mfma_f32_16x16x32_bf16 v[8:11], v[170:173], v[204:207], v[8:11]
	v_mfma_f32_16x16x32_bf16 v[60:63], v[144:147], v[212:215], v[60:63]
	v_mfma_f32_16x16x32_bf16 v[0:3], v[170:173], v[212:215], v[0:3]
	v_mfma_f32_16x16x32_bf16 v[88:91], v[148:151], v[192:195], v[88:91]
	v_mfma_f32_16x16x32_bf16 v[24:27], v[174:177], v[192:195], v[24:27]
	v_mfma_f32_16x16x32_bf16 v[80:83], v[148:151], v[200:203], v[80:83]
	v_mfma_f32_16x16x32_bf16 v[16:19], v[174:177], v[200:203], v[16:19]
	v_mfma_f32_16x16x32_bf16 v[72:75], v[148:151], v[208:211], v[72:75]
	v_mfma_f32_16x16x32_bf16 v[8:11], v[174:177], v[208:211], v[8:11]
	v_mfma_f32_16x16x32_bf16 v[60:63], v[148:151], v[216:219], v[60:63]
	v_mfma_f32_16x16x32_bf16 v[0:3], v[174:177], v[216:219], v[0:3]
	s_barrier
; #define PG8_STAGE(bufoff, gbase, voff) do { _Pragma("unroll") for (int _i = 0; _i < 2; ++_i) \
;         __builtin_amdgcn_global_load_lds((const unsigned*)((const char*)(gbase) + (voff)[_i]), (LAS unsigned*)(lds + (bufoff) + ldsw + _i * 8192), 16, 0, 0); } while (0)
; #define PG8_LDA(dst, b, h) do { _Pragma("unroll") for (int m = 0; m < 4; ++m) _Pragma("unroll") for (int k = 0; k < 2; ++k) dst[m][k] = *(const LAS bf16x8*)(lds + PG8_SA(b, h) + aoff + m * 2048 + k * 1024); } while (0)
; #define PG8_LDB(dst, b, h) do { _Pragma("unroll") for (int n = 0; n < 2; ++n) _Pragma("unroll") for (int k = 0; k < 2; ++k) dst[n][k] = *(const LAS bf16x8*)(lds + PG8_SB(b, h) + boff + n * 2048 + k * 1024); } while (0)
; #define PG8_MMA(ai, bj, At, Bt) do { __builtin_amdgcn_s_setprio(1); _Pragma("unroll") for (int m = 0; m < 4; ++m) _Pragma("unroll") for (int n = 0; n < 2; ++n) _Pragma("unroll") for (int k = 0; k < 2; ++k) \
;         acc[ai][bj][m][n] = __builtin_amdgcn_mfma_f32_16x16x32_bf16(Bt[n][k], At[m][k], acc[ai][bj][m][n], 0, 0, 0); __builtin_amdgcn_s_setprio(0); } while (0)
; #define PG8_WAIT_V(n) asm volatile("s_waitcnt vmcnt(" #n ")" ::: "memory")
; #define PG8_WAIT_L(n) asm volatile("s_waitcnt lgkmcnt(" #n ")" ::: "memory")
; #define PG8_BAR __builtin_amdgcn_s_barrier()
; #define PG8_SCHED __builtin_amdgcn_sched_barrier(0)
; template <class Epi, class Sched, bool ALIGN_EPI = true>
; __device__ __forceinline__ void gemm_phase(LAS unsigned char* lds, const Gemm g, const Sched& S, const Epi& E) {
;     ...
;             PG8_LDB(B0, 1, 0); PG8_LDB(B1, 1, 1); PG8_SCHED; PG8_LDA(At, 1, 0); PG8_STAGE(PG8_SA(0, 1), a2 + hsA, voffA);
;             PG8_WAIT_V(8); PG8_WAIT_L(0); PG8_BAR; PG8_MMA(0, 0, At, B0); PG8_MMA(0, 1, At, B1); PG8_BAR; PG8_SCHED;
	s_add_i32 s36, 0, 0x18000
	s_add_i32 s37, 0, 0x1c000
	v_add_u32_e32 v132, s36, v182
	v_add_u32_e32 v174, s37, v182
	ds_read_b128 v[116:119], v132
	ds_read_b128 v[120:123], v132 offset:1024
	ds_read_b128 v[128:131], v132 offset:2048
	ds_read_b128 v[132:135], v132 offset:3072
	ds_read_b128 v[144:147], v174
	ds_read_b128 v[148:151], v174 offset:1024
	ds_read_b128 v[170:173], v174 offset:2048
	ds_read_b128 v[174:177], v174 offset:3072
	s_add_u32 s28, s28, 0x40000
	s_addc_u32 s29, s29, 0
	s_mov_b32 m0, s44
	v_lshl_add_u64 v[226:227], s[28:29], 0, v[154:155]
	ds_read_b128 v[188:191], v186 offset:32768
	ds_read_b128 v[192:195], v186 offset:33792
	ds_read_b128 v[196:199], v186 offset:34816
	ds_read_b128 v[200:203], v186 offset:35840
	ds_read_b128 v[204:207], v186 offset:36864
	ds_read_b128 v[208:211], v186 offset:37888
	ds_read_b128 v[212:215], v186 offset:38912
	ds_read_b128 v[216:219], v186 offset:39936
	global_load_lds_dwordx4 v[226:227], off
	v_lshl_add_u64 v[226:227], s[28:29], 0, v[158:159]
	s_mov_b32 m0, s45
	s_nop 0
	global_load_lds_dwordx4 v[226:227], off
	s_waitcnt vmcnt(8)
	s_waitcnt lgkmcnt(0)
	s_barrier
	s_waitcnt lgkmcnt(0)
	v_mfma_f32_16x16x32_bf16 v[140:143], v[116:119], v[188:191], v[140:143]
	v_mfma_f32_16x16x32_bf16 v[64:67], v[128:131], v[188:191], v[64:67]
	v_mfma_f32_16x16x32_bf16 v[124:127], v[116:119], v[196:199], v[124:127]
	v_mfma_f32_16x16x32_bf16 v[52:55], v[128:131], v[196:199], v[52:55]
	v_mfma_f32_16x16x32_bf16 v[108:111], v[116:119], v[204:207], v[108:111]
	v_mfma_f32_16x16x32_bf16 v[44:47], v[128:131], v[204:207], v[44:47]
	v_mfma_f32_16x16x32_bf16 v[100:103], v[116:119], v[212:215], v[100:103]
	v_mfma_f32_16x16x32_bf16 v[36:39], v[128:131], v[212:215], v[36:39]
	v_mfma_f32_16x16x32_bf16 v[140:143], v[120:123], v[192:195], v[140:143]
	v_mfma_f32_16x16x32_bf16 v[64:67], v[132:135], v[192:195], v[64:67]
	v_mfma_f32_16x16x32_bf16 v[124:127], v[120:123], v[200:203], v[124:127]
	v_mfma_f32_16x16x32_bf16 v[52:55], v[132:135], v[200:203], v[52:55]
	v_mfma_f32_16x16x32_bf16 v[108:111], v[120:123], v[208:211], v[108:111]
	v_mfma_f32_16x16x32_bf16 v[44:47], v[132:135], v[208:211], v[44:47]
	v_mfma_f32_16x16x32_bf16 v[100:103], v[120:123], v[216:219], v[100:103]
	v_mfma_f32_16x16x32_bf16 v[36:39], v[132:135], v[216:219], v[36:39]
	v_mfma_f32_16x16x32_bf16 v[136:139], v[144:147], v[188:191], v[136:139]
	v_mfma_f32_16x16x32_bf16 v[56:59], v[170:173], v[188:191], v[56:59]
	v_mfma_f32_16x16x32_bf16 v[112:115], v[144:147], v[196:199], v[112:115]
	v_mfma_f32_16x16x32_bf16 v[48:51], v[170:173], v[196:199], v[48:51]
	v_mfma_f32_16x16x32_bf16 v[104:107], v[144:147], v[204:207], v[104:107]
	v_mfma_f32_16x16x32_bf16 v[40:43], v[170:173], v[204:207], v[40:43]
	v_mfma_f32_16x16x32_bf16 v[96:99], v[144:147], v[212:215], v[96:99]
	v_mfma_f32_16x16x32_bf16 v[32:35], v[170:173], v[212:215], v[32:35]
	v_mfma_f32_16x16x32_bf16 v[136:139], v[148:151], v[192:195], v[136:139]
	v_mfma_f32_16x16x32_bf16 v[56:59], v[174:177], v[192:195], v[56:59]
	v_mfma_f32_16x16x32_bf16 v[112:115], v[148:151], v[200:203], v[112:115]
	v_mfma_f32_16x16x32_bf16 v[48:51], v[174:177], v[200:203], v[48:51]
	v_mfma_f32_16x16x32_bf16 v[104:107], v[148:151], v[208:211], v[104:107]
	v_mfma_f32_16x16x32_bf16 v[40:43], v[174:177], v[208:211], v[40:43]
	v_mfma_f32_16x16x32_bf16 v[96:99], v[148:151], v[216:219], v[96:99]
	v_mfma_f32_16x16x32_bf16 v[32:35], v[174:177], v[216:219], v[32:35]
	s_barrier
; #define PG8_STAGE(bufoff, gbase, voff) do { _Pragma("unroll") for (int _i = 0; _i < 2; ++_i) \
;         __builtin_amdgcn_global_load_lds((const unsigned*)((const char*)(gbase) + (voff)[_i]), (LAS unsigned*)(lds + (bufoff) + ldsw + _i * 8192), 16, 0, 0); } while (0)
; #define PG8_LDA(dst, b, h) do { _Pragma("unroll") for (int m = 0; m < 4; ++m) _Pragma("unroll") for (int k = 0; k < 2; ++k) dst[m][k] = *(const LAS bf16x8*)(lds + PG8_SA(b, h) + aoff + m * 2048 + k * 1024); } while (0)
; #define PG8_MMA(ai, bj, At, Bt) do { __builtin_amdgcn_s_setprio(1); _Pragma("unroll") for (int m = 0; m < 4; ++m) _Pragma("unroll") for (int n = 0; n < 2; ++n) _Pragma("unroll") for (int k = 0; k < 2; ++k) \
;         acc[ai][bj][m][n] = __builtin_amdgcn_mfma_f32_16x16x32_bf16(Bt[n][k], At[m][k], acc[ai][bj][m][n], 0, 0, 0); __builtin_amdgcn_s_setprio(0); } while (0)
; #define PG8_WAIT_V(n) asm volatile("s_waitcnt vmcnt(" #n ")" ::: "memory")
; #define PG8_WAIT_L(n) asm volatile("s_waitcnt lgkmcnt(" #n ")" ::: "memory")
; #define PG8_BAR __builtin_amdgcn_s_barrier()
; #define PG8_SCHED __builtin_amdgcn_sched_barrier(0)
; template <class Epi, class Sched, bool ALIGN_EPI = true>
; __device__ __forceinline__ void gemm_phase(LAS unsigned char* lds, const Gemm g, const Sched& S, const Epi& E) {
;     ...
;             PG8_LDA(At, 1, 1); PG8_STAGE(PG8_SB(1, 0), b3, voffB); PG8_STAGE(PG8_SB(1, 1), b3 + hsB, voffB); PG8_STAGE(PG8_SA(1, 0), a3, voffA);
;             PG8_WAIT_V(8); PG8_WAIT_L(0); PG8_BAR; PG8_MMA(1, 0, At, B0); PG8_MMA(1, 1, At, B1); PG8_BAR; PG8_SCHED;
;         }
;         if constexpr (ALIGN_EPI) { if (wr == 0) PG8_BAR; }
	s_add_i32 s28, s36, s33
	v_lshl_add_u64 v[178:179], v[178:179], 0, s[94:95]
	s_mov_b32 m0, s28
	ds_read_b128 v[188:191], v186 offset:49152
	ds_read_b128 v[192:195], v186 offset:50176
	ds_read_b128 v[196:199], v186 offset:51200
	ds_read_b128 v[200:203], v186 offset:52224
	ds_read_b128 v[204:207], v186 offset:53248
	ds_read_b128 v[208:211], v186 offset:54272
	ds_read_b128 v[212:215], v186 offset:55296
	ds_read_b128 v[216:219], v186 offset:56320
	global_load_lds_dwordx4 v[178:179], off
	s_add_i32 m0, s28, 0x2000
	s_add_u32 s26, s26, 0x40080
	v_lshl_add_u64 v[178:179], v[220:221], 0, s[94:95]
	s_addc_u32 s27, s27, 0
	s_add_i32 s28, s37, s33
	global_load_lds_dwordx4 v[178:179], off
	v_lshl_add_u64 v[178:179], s[26:27], 0, v[156:157]
	s_mov_b32 m0, s28
	s_nop 0
	global_load_lds_dwordx4 v[178:179], off
	v_lshl_add_u64 v[178:179], s[26:27], 0, v[160:161]
	s_add_i32 m0, s28, 0x2000
	s_nop 0
	global_load_lds_dwordx4 v[178:179], off
	v_lshl_add_u64 v[178:179], v[222:223], 0, s[94:95]
	s_mov_b32 m0, s48
	s_nop 0
	global_load_lds_dwordx4 v[178:179], off
	v_lshl_add_u64 v[178:179], v[224:225], 0, s[94:95]
	s_mov_b32 m0, s49
	s_nop 0
	global_load_lds_dwordx4 v[178:179], off
	s_waitcnt vmcnt(8)
	s_waitcnt lgkmcnt(0)
	s_barrier
	s_waitcnt lgkmcnt(0)
	v_mfma_f32_16x16x32_bf16 v[92:95], v[116:119], v[188:191], v[92:95]
	v_mfma_f32_16x16x32_bf16 v[28:31], v[128:131], v[188:191], v[28:31]
	v_mfma_f32_16x16x32_bf16 v[84:87], v[116:119], v[196:199], v[84:87]
	v_mfma_f32_16x16x32_bf16 v[20:23], v[128:131], v[196:199], v[20:23]
	v_mfma_f32_16x16x32_bf16 v[76:79], v[116:119], v[204:207], v[76:79]
	v_mfma_f32_16x16x32_bf16 v[12:15], v[128:131], v[204:207], v[12:15]
	v_mfma_f32_16x16x32_bf16 v[68:71], v[116:119], v[212:215], v[68:71]
	v_mfma_f32_16x16x32_bf16 v[4:7], v[128:131], v[212:215], v[4:7]
	v_mfma_f32_16x16x32_bf16 v[92:95], v[120:123], v[192:195], v[92:95]
	v_mfma_f32_16x16x32_bf16 v[28:31], v[132:135], v[192:195], v[28:31]
	v_mfma_f32_16x16x32_bf16 v[84:87], v[120:123], v[200:203], v[84:87]
	v_mfma_f32_16x16x32_bf16 v[20:23], v[132:135], v[200:203], v[20:23]
	v_mfma_f32_16x16x32_bf16 v[76:79], v[120:123], v[208:211], v[76:79]
	v_mfma_f32_16x16x32_bf16 v[12:15], v[132:135], v[208:211], v[12:15]
	v_mfma_f32_16x16x32_bf16 v[68:71], v[120:123], v[216:219], v[68:71]
	v_mfma_f32_16x16x32_bf16 v[4:7], v[132:135], v[216:219], v[4:7]
	v_mfma_f32_16x16x32_bf16 v[88:91], v[144:147], v[188:191], v[88:91]
	v_mfma_f32_16x16x32_bf16 v[24:27], v[170:173], v[188:191], v[24:27]
	v_mfma_f32_16x16x32_bf16 v[80:83], v[144:147], v[196:199], v[80:83]
	v_mfma_f32_16x16x32_bf16 v[16:19], v[170:173], v[196:199], v[16:19]
	v_mfma_f32_16x16x32_bf16 v[72:75], v[144:147], v[204:207], v[72:75]
	v_mfma_f32_16x16x32_bf16 v[8:11], v[170:173], v[204:207], v[8:11]
	v_mfma_f32_16x16x32_bf16 v[60:63], v[144:147], v[212:215], v[60:63]
	v_mfma_f32_16x16x32_bf16 v[0:3], v[170:173], v[212:215], v[0:3]
	v_mfma_f32_16x16x32_bf16 v[88:91], v[148:151], v[192:195], v[88:91]
	v_mfma_f32_16x16x32_bf16 v[24:27], v[174:177], v[192:195], v[24:27]
	v_mfma_f32_16x16x32_bf16 v[80:83], v[148:151], v[200:203], v[80:83]
	v_mfma_f32_16x16x32_bf16 v[16:19], v[174:177], v[200:203], v[16:19]
	v_mfma_f32_16x16x32_bf16 v[72:75], v[148:151], v[208:211], v[72:75]
	v_mfma_f32_16x16x32_bf16 v[8:11], v[174:177], v[208:211], v[8:11]
	v_mfma_f32_16x16x32_bf16 v[60:63], v[148:151], v[216:219], v[60:63]
	v_mfma_f32_16x16x32_bf16 v[0:3], v[174:177], v[216:219], v[0:3]
	s_barrier
	s_add_i32 s35, s35, 2
	s_add_u32 s6, s6, 0x100
	s_addc_u32 s7, s7, 0
	s_add_u32 s31, s31, 0x100
	s_addc_u32 s34, s34, 0
	s_cmp_gt_u32 s35, 13
	s_cbranch_scc0 .LBB0_881
	s_setprio 0
	s_and_b64 vcc, exec, s[96:97]
	s_cbranch_vccz .LBB0_884
	s_barrier

; #define PG8_STAGE(bufoff, gbase, voff) do { _Pragma("unroll") for (int _i = 0; _i < 2; ++_i) \
;         __builtin_amdgcn_global_load_lds((const unsigned*)((const char*)(gbase) + (voff)[_i]), (LAS unsigned*)(lds + (bufoff) + ldsw + _i * 8192), 16, 0, 0); } while (0)
; #define PG8_LDA(dst, b, h) do { _Pragma("unroll") for (int m = 0; m < 4; ++m) _Pragma("unroll") for (int k = 0; k < 2; ++k) dst[m][k] = *(const LAS bf16x8*)(lds + PG8_SA(b, h) + aoff + m * 2048 + k * 1024); } while (0)
; #define PG8_LDB(dst, b, h) do { _Pragma("unroll") for (int n = 0; n < 2; ++n) _Pragma("unroll") for (int k = 0; k < 2; ++k) dst[n][k] = *(const LAS bf16x8*)(lds + PG8_SB(b, h) + boff + n * 2048 + k * 1024); } while (0)
; #define PG8_MMA(ai, bj, At, Bt) do { __builtin_amdgcn_s_setprio(1); _Pragma("unroll") for (int m = 0; m < 4; ++m) _Pragma("unroll") for (int n = 0; n < 2; ++n) _Pragma("unroll") for (int k = 0; k < 2; ++k) \
;         acc[ai][bj][m][n] = __builtin_amdgcn_mfma_f32_16x16x32_bf16(Bt[n][k], At[m][k], acc[ai][bj][m][n], 0, 0, 0); __builtin_amdgcn_s_setprio(0); } while (0)
; template <class Epi, class Sched, bool ALIGN_EPI = true>
; __device__ __forceinline__ void gemm_phase(LAS unsigned char* lds, const Gemm g, const Sched& S, const Epi& E) {
;     ...
;         const bool has_next = S.next(ui + 1, nxt);
;         const char* nA = has_next ? (const char*)g.A + ((long)nxt.pm * g.mstride + g.moff) * (long)(g.lda * 2) : cA; const char* nB = has_next ? (const char*)g.Bt + (size_t)nxt.pn * tsB : cB;
;         for (int t = 0; t < nt; t += 2) {
;             const bool last = (t == nt - 2);
;             const char* a1 = cA + (size_t)(t + 1) * kstep;
;             const char* a2 = last ? nA : cA + (size_t)(t + 2) * kstep; const char* b2 = last ? nB : cB + (size_t)(t + 2) * kstep;
;             const char* a3 = a2 + kstep; const char* b3 = b2 + kstep;
;             PG8_LDB(B0, 0, 0); PG8_LDB(B1, 0, 1); PG8_SCHED; PG8_LDA(At, 0, 0); PG8_STAGE(PG8_SA(1, 1), a1 + hsA, voffA);
;             PG8_WAIT_V(8); PG8_WAIT_L(0); PG8_BAR; PG8_MMA(0, 0, At, B0); PG8_MMA(0, 1, At, B1); PG8_BAR; PG8_SCHED;
;     ...
;         for (int a = 0; a < 2; ++a)
; #pragma unroll
;             for (int b = 0; b < 2; ++b)
; #pragma unroll
;                 for (int m = 0; m < 4; ++m)
; #pragma unroll
;                     for (int n = 0; n < 2; ++n) acc[a][b][m][n] = (f32x4){0.f, 0.f, 0.f, 0.f};
.LBB0_998:
	s_add_u32 s51, s28, 0x100
	v_mov_b32_e32 v0, 0
	s_addc_u32 s52, s29, 0
	s_mov_b32 s53, -2
	v_mov_b32_e32 v1, v0
	v_mov_b32_e32 v2, v0
	v_mov_b32_e32 v3, v0
	v_mov_b32_e32 v4, v0
	v_mov_b32_e32 v5, v0
	v_mov_b32_e32 v6, v0
	v_mov_b32_e32 v7, v0
	v_mov_b32_e32 v12, v0
	v_mov_b32_e32 v13, v0
	v_mov_b32_e32 v14, v0
	v_mov_b32_e32 v15, v0
	v_mov_b32_e32 v20, v0
	v_mov_b32_e32 v21, v0
	v_mov_b32_e32 v22, v0
	v_mov_b32_e32 v23, v0
	v_mov_b32_e32 v28, v0
	v_mov_b32_e32 v29, v0
	v_mov_b32_e32 v30, v0
	v_mov_b32_e32 v31, v0
	v_mov_b32_e32 v36, v0
	v_mov_b32_e32 v37, v0
	v_mov_b32_e32 v38, v0
	v_mov_b32_e32 v39, v0
	v_mov_b32_e32 v44, v0
	v_mov_b32_e32 v45, v0
	v_mov_b32_e32 v46, v0
	v_mov_b32_e32 v47, v0
	v_mov_b32_e32 v52, v0
	v_mov_b32_e32 v53, v0
	v_mov_b32_e32 v54, v0
	v_mov_b32_e32 v55, v0
	v_mov_b32_e32 v8, v0
	v_mov_b32_e32 v9, v0
	v_mov_b32_e32 v10, v0
	v_mov_b32_e32 v11, v0
	v_mov_b32_e32 v16, v0
	v_mov_b32_e32 v17, v0
	v_mov_b32_e32 v18, v0
	v_mov_b32_e32 v19, v0
	v_mov_b32_e32 v24, v0
	v_mov_b32_e32 v25, v0
	v_mov_b32_e32 v26, v0
	v_mov_b32_e32 v27, v0
	v_mov_b32_e32 v32, v0
	v_mov_b32_e32 v33, v0
	v_mov_b32_e32 v34, v0
	v_mov_b32_e32 v35, v0
	v_mov_b32_e32 v40, v0
	v_mov_b32_e32 v41, v0
	v_mov_b32_e32 v42, v0
	v_mov_b32_e32 v43, v0
	v_mov_b32_e32 v48, v0
	v_mov_b32_e32 v49, v0
	v_mov_b32_e32 v50, v0
	v_mov_b32_e32 v51, v0
	v_mov_b32_e32 v56, v0
	v_mov_b32_e32 v57, v0
	v_mov_b32_e32 v58, v0
	v_mov_b32_e32 v59, v0
	v_mov_b32_e32 v60, v0
	v_mov_b32_e32 v61, v0
	v_mov_b32_e32 v62, v0
	v_mov_b32_e32 v63, v0
	v_mov_b32_e32 v64, v0
	v_mov_b32_e32 v65, v0
	v_mov_b32_e32 v66, v0
	v_mov_b32_e32 v67, v0
	v_mov_b32_e32 v68, v0
	v_mov_b32_e32 v69, v0
	v_mov_b32_e32 v70, v0
	v_mov_b32_e32 v71, v0
	v_mov_b32_e32 v76, v0
	v_mov_b32_e32 v77, v0
	v_mov_b32_e32 v78, v0
	v_mov_b32_e32 v79, v0
	v_mov_b32_e32 v84, v0
	v_mov_b32_e32 v85, v0
	v_mov_b32_e32 v86, v0
	v_mov_b32_e32 v87, v0
	v_mov_b32_e32 v92, v0
	v_mov_b32_e32 v93, v0
	v_mov_b32_e32 v94, v0
	v_mov_b32_e32 v95, v0
	v_mov_b32_e32 v100, v0
	v_mov_b32_e32 v101, v0
	v_mov_b32_e32 v102, v0
	v_mov_b32_e32 v103, v0
	v_mov_b32_e32 v108, v0
	v_mov_b32_e32 v109, v0
	v_mov_b32_e32 v110, v0
	v_mov_b32_e32 v111, v0
	v_mov_b32_e32 v116, v0
	v_mov_b32_e32 v117, v0
	v_mov_b32_e32 v118, v0
	v_mov_b32_e32 v119, v0
	v_mov_b32_e32 v72, v0
	v_mov_b32_e32 v73, v0
	v_mov_b32_e32 v74, v0
	v_mov_b32_e32 v75, v0
	v_mov_b32_e32 v80, v0
	v_mov_b32_e32 v81, v0
	v_mov_b32_e32 v82, v0
	v_mov_b32_e32 v83, v0
	v_mov_b32_e32 v88, v0
	v_mov_b32_e32 v89, v0
	v_mov_b32_e32 v90, v0
	v_mov_b32_e32 v91, v0
	v_mov_b32_e32 v96, v0
	v_mov_b32_e32 v97, v0
	v_mov_b32_e32 v98, v0
	v_mov_b32_e32 v99, v0
	v_mov_b32_e32 v104, v0
	v_mov_b32_e32 v105, v0
	v_mov_b32_e32 v106, v0
	v_mov_b32_e32 v107, v0
	v_mov_b32_e32 v112, v0
	v_mov_b32_e32 v113, v0
	v_mov_b32_e32 v114, v0
	v_mov_b32_e32 v115, v0
	v_mov_b32_e32 v120, v0
	v_mov_b32_e32 v121, v0
	v_mov_b32_e32 v122, v0
	v_mov_b32_e32 v123, v0
	v_mov_b32_e32 v124, v0
	v_mov_b32_e32 v125, v0
	v_mov_b32_e32 v126, v0
	v_mov_b32_e32 v127, v0
	v_readfirstlane_b32 s98, v181
	s_lshr_b32 s98, s98, 8
	s_cmp_eq_u32 s98, 0
	s_cbranch_scc1 .LprioK4
	s_setprio 1
.LprioK4:
.LBB0_999:
	ds_read_b128 v[144:147], v156
	ds_read_b128 v[148:151], v156 offset:1024
	ds_read_b128 v[160:163], v156 offset:2048
	ds_read_b128 v[164:167], v156 offset:3072
	ds_read_b128 v[168:171], v157
	ds_read_b128 v[172:175], v157 offset:1024
	ds_read_b128 v[176:179], v157 offset:2048
	ds_read_b128 v[182:185], v157 offset:3072
	s_add_u32 s4, s26, 0x100
	s_addc_u32 s5, s27, 0
	s_cmp_eq_u32 s53, 40
	s_cselect_b32 s31, s23, s5
	s_cselect_b32 s30, s22, s4
	s_cselect_b32 s29, s25, s52
	s_cselect_b32 s28, s24, s51
	v_lshl_add_u64 v[218:219], s[26:27], 0, v[136:137]
	s_add_i32 m0, s34, 0xc000
	ds_read_b128 v[186:189], v158
	ds_read_b128 v[190:193], v158 offset:1024
	ds_read_b128 v[194:197], v158 offset:2048
	ds_read_b128 v[198:201], v158 offset:3072
	ds_read_b128 v[202:205], v158 offset:4096
	ds_read_b128 v[206:209], v158 offset:5120
	ds_read_b128 v[210:213], v158 offset:6144
	ds_read_b128 v[214:217], v158 offset:7168
	global_load_lds_dwordx4 v[218:219], off
	v_lshl_add_u64 v[218:219], s[26:27], 0, v[138:139]
	s_add_i32 m0, s34, 0xe000
	s_nop 0
	global_load_lds_dwordx4 v[218:219], off
	s_waitcnt vmcnt(8)
	s_waitcnt lgkmcnt(0)
	s_barrier
	s_waitcnt lgkmcnt(0)
	v_mfma_f32_16x16x32_bf16 v[124:127], v[144:147], v[186:189], v[124:127]
	v_mfma_f32_16x16x32_bf16 v[120:123], v[160:163], v[186:189], v[120:123]
	v_mfma_f32_16x16x32_bf16 v[112:115], v[144:147], v[194:197], v[112:115]
	v_mfma_f32_16x16x32_bf16 v[104:107], v[160:163], v[194:197], v[104:107]
	v_mfma_f32_16x16x32_bf16 v[96:99], v[144:147], v[202:205], v[96:99]
	v_mfma_f32_16x16x32_bf16 v[88:91], v[160:163], v[202:205], v[88:91]
	v_mfma_f32_16x16x32_bf16 v[80:83], v[144:147], v[210:213], v[80:83]
	v_mfma_f32_16x16x32_bf16 v[72:75], v[160:163], v[210:213], v[72:75]
	v_mfma_f32_16x16x32_bf16 v[124:127], v[148:151], v[190:193], v[124:127]
	v_mfma_f32_16x16x32_bf16 v[120:123], v[164:167], v[190:193], v[120:123]
	v_mfma_f32_16x16x32_bf16 v[112:115], v[148:151], v[198:201], v[112:115]
	v_mfma_f32_16x16x32_bf16 v[104:107], v[164:167], v[198:201], v[104:107]
	v_mfma_f32_16x16x32_bf16 v[96:99], v[148:151], v[206:209], v[96:99]
	v_mfma_f32_16x16x32_bf16 v[88:91], v[164:167], v[206:209], v[88:91]
	v_mfma_f32_16x16x32_bf16 v[80:83], v[148:151], v[214:217], v[80:83]
	v_mfma_f32_16x16x32_bf16 v[72:75], v[164:167], v[214:217], v[72:75]
	v_mfma_f32_16x16x32_bf16 v[116:119], v[168:171], v[186:189], v[116:119]
	v_mfma_f32_16x16x32_bf16 v[108:111], v[176:179], v[186:189], v[108:111]
	v_mfma_f32_16x16x32_bf16 v[100:103], v[168:171], v[194:197], v[100:103]
	v_mfma_f32_16x16x32_bf16 v[92:95], v[176:179], v[194:197], v[92:95]
	v_mfma_f32_16x16x32_bf16 v[84:87], v[168:171], v[202:205], v[84:87]
	v_mfma_f32_16x16x32_bf16 v[76:79], v[176:179], v[202:205], v[76:79]
	v_mfma_f32_16x16x32_bf16 v[68:71], v[168:171], v[210:213], v[68:71]
	v_mfma_f32_16x16x32_bf16 v[64:67], v[176:179], v[210:213], v[64:67]
	v_mfma_f32_16x16x32_bf16 v[116:119], v[172:175], v[190:193], v[116:119]
	v_mfma_f32_16x16x32_bf16 v[108:111], v[182:185], v[190:193], v[108:111]
	v_mfma_f32_16x16x32_bf16 v[100:103], v[172:175], v[198:201], v[100:103]
	v_mfma_f32_16x16x32_bf16 v[92:95], v[182:185], v[198:201], v[92:95]
	v_mfma_f32_16x16x32_bf16 v[84:87], v[172:175], v[206:209], v[84:87]
	v_mfma_f32_16x16x32_bf16 v[76:79], v[182:185], v[206:209], v[76:79]
	v_mfma_f32_16x16x32_bf16 v[68:71], v[172:175], v[214:217], v[68:71]
	v_mfma_f32_16x16x32_bf16 v[64:67], v[182:185], v[214:217], v[64:67]
	s_barrier
; #define PG8_STAGE(bufoff, gbase, voff) do { _Pragma("unroll") for (int _i = 0; _i < 2; ++_i) \
;         __builtin_amdgcn_global_load_lds((const unsigned*)((const char*)(gbase) + (voff)[_i]), (LAS unsigned*)(lds + (bufoff) + ldsw + _i * 8192), 16, 0, 0); } while (0)
; #define PG8_LDA(dst, b, h) do { _Pragma("unroll") for (int m = 0; m < 4; ++m) _Pragma("unroll") for (int k = 0; k < 2; ++k) dst[m][k] = *(const LAS bf16x8*)(lds + PG8_SA(b, h) + aoff + m * 2048 + k * 1024); } while (0)
; #define PG8_LDB(dst, b, h) do { _Pragma("unroll") for (int n = 0; n < 2; ++n) _Pragma("unroll") for (int k = 0; k < 2; ++k) dst[n][k] = *(const LAS bf16x8*)(lds + PG8_SB(b, h) + boff + n * 2048 + k * 1024); } while (0)
; #define PG8_MMA(ai, bj, At, Bt) do { __builtin_amdgcn_s_setprio(1); _Pragma("unroll") for (int m = 0; m < 4; ++m) _Pragma("unroll") for (int n = 0; n < 2; ++n) _Pragma("unroll") for (int k = 0; k < 2; ++k) \
;         acc[ai][bj][m][n] = __builtin_amdgcn_mfma_f32_16x16x32_bf16(Bt[n][k], At[m][k], acc[ai][bj][m][n], 0, 0, 0); __builtin_amdgcn_s_setprio(0); } while (0)
; #define PG8_WAIT_V(n) asm volatile("s_waitcnt vmcnt(" #n ")" ::: "memory")
; #define PG8_WAIT_L(n) asm volatile("s_waitcnt lgkmcnt(" #n ")" ::: "memory")
; #define PG8_BAR __builtin_amdgcn_s_barrier()
; #define PG8_SCHED __builtin_amdgcn_sched_barrier(0)
; template <class Epi, class Sched, bool ALIGN_EPI = true>
; __device__ __forceinline__ void gemm_phase(LAS unsigned char* lds, const Gemm g, const Sched& S, const Epi& E) {
;     ...
;             PG8_LDA(At, 0, 1); PG8_STAGE(PG8_SB(0, 0), b2, voffB); PG8_STAGE(PG8_SB(0, 1), b2 + hsB, voffB); PG8_STAGE(PG8_SA(0, 0), a2, voffA);
;             PG8_WAIT_V(8); PG8_WAIT_L(0); PG8_BAR; PG8_MMA(1, 0, At, B0); PG8_MMA(1, 1, At, B1); PG8_BAR; PG8_SCHED;
;             PG8_LDB(B0, 1, 0); PG8_LDB(B1, 1, 1); PG8_SCHED; PG8_LDA(At, 1, 0); PG8_STAGE(PG8_SA(0, 1), a2 + hsA, voffA);
;             PG8_WAIT_V(8); PG8_WAIT_L(0); PG8_BAR; PG8_MMA(0, 0, At, B0); PG8_MMA(0, 1, At, B1); PG8_BAR; PG8_SCHED;
	s_add_i32 s26, s45, s33
	v_lshl_add_u64 v[218:219], s[28:29], 0, v[130:131]
	s_mov_b32 m0, s26
	ds_read_b128 v[186:189], v158 offset:16384
	ds_read_b128 v[190:193], v158 offset:17408
	ds_read_b128 v[194:197], v158 offset:18432
	ds_read_b128 v[198:201], v158 offset:19456
	ds_read_b128 v[202:205], v158 offset:20480
	ds_read_b128 v[206:209], v158 offset:21504
	ds_read_b128 v[210:213], v158 offset:22528
	ds_read_b128 v[214:217], v158 offset:23552
	global_load_lds_dwordx4 v[218:219], off
	s_add_i32 m0, s26, 0x2000
	s_add_u32 s26, s28, 0xb0000
	v_lshl_add_u64 v[220:221], s[28:29], 0, v[134:135]
	s_addc_u32 s27, s29, 0
	s_add_i32 s54, s46, s33
	global_load_lds_dwordx4 v[220:221], off
	v_lshl_add_u64 v[222:223], s[26:27], 0, v[130:131]
	s_mov_b32 m0, s54
	v_lshl_add_u64 v[224:225], s[30:31], 0, v[132:133]
	global_load_lds_dwordx4 v[222:223], off
	v_lshl_add_u64 v[222:223], s[26:27], 0, v[134:135]
	s_add_i32 m0, s54, 0x2000
	s_nop 0
	global_load_lds_dwordx4 v[222:223], off
	v_lshl_add_u64 v[222:223], s[30:31], 0, v[128:129]
	s_mov_b32 m0, s34
	s_nop 0
	global_load_lds_dwordx4 v[222:223], off
	s_mov_b32 m0, s35
	s_nop 0
	global_load_lds_dwordx4 v[224:225], off
	s_waitcnt vmcnt(8)
	s_waitcnt lgkmcnt(0)
	s_barrier
	s_waitcnt lgkmcnt(0)
	v_mfma_f32_16x16x32_bf16 v[60:63], v[144:147], v[186:189], v[60:63]
	v_mfma_f32_16x16x32_bf16 v[56:59], v[160:163], v[186:189], v[56:59]
	v_mfma_f32_16x16x32_bf16 v[48:51], v[144:147], v[194:197], v[48:51]
	v_mfma_f32_16x16x32_bf16 v[40:43], v[160:163], v[194:197], v[40:43]
	v_mfma_f32_16x16x32_bf16 v[32:35], v[144:147], v[202:205], v[32:35]
	v_mfma_f32_16x16x32_bf16 v[24:27], v[160:163], v[202:205], v[24:27]
	v_mfma_f32_16x16x32_bf16 v[16:19], v[144:147], v[210:213], v[16:19]
	v_mfma_f32_16x16x32_bf16 v[8:11], v[160:163], v[210:213], v[8:11]
	v_mfma_f32_16x16x32_bf16 v[60:63], v[148:151], v[190:193], v[60:63]
	v_mfma_f32_16x16x32_bf16 v[56:59], v[164:167], v[190:193], v[56:59]
	v_mfma_f32_16x16x32_bf16 v[48:51], v[148:151], v[198:201], v[48:51]
	v_mfma_f32_16x16x32_bf16 v[40:43], v[164:167], v[198:201], v[40:43]
	v_mfma_f32_16x16x32_bf16 v[32:35], v[148:151], v[206:209], v[32:35]
	v_mfma_f32_16x16x32_bf16 v[24:27], v[164:167], v[206:209], v[24:27]
	v_mfma_f32_16x16x32_bf16 v[16:19], v[148:151], v[214:217], v[16:19]
	v_mfma_f32_16x16x32_bf16 v[8:11], v[164:167], v[214:217], v[8:11]
	v_mfma_f32_16x16x32_bf16 v[52:55], v[168:171], v[186:189], v[52:55]
	v_mfma_f32_16x16x32_bf16 v[44:47], v[176:179], v[186:189], v[44:47]
	v_mfma_f32_16x16x32_bf16 v[36:39], v[168:171], v[194:197], v[36:39]
	v_mfma_f32_16x16x32_bf16 v[28:31], v[176:179], v[194:197], v[28:31]
	v_mfma_f32_16x16x32_bf16 v[20:23], v[168:171], v[202:205], v[20:23]
	v_mfma_f32_16x16x32_bf16 v[12:15], v[176:179], v[202:205], v[12:15]
	v_mfma_f32_16x16x32_bf16 v[4:7], v[168:171], v[210:213], v[4:7]
	v_mfma_f32_16x16x32_bf16 v[0:3], v[176:179], v[210:213], v[0:3]
	v_mfma_f32_16x16x32_bf16 v[52:55], v[172:175], v[190:193], v[52:55]
	v_mfma_f32_16x16x32_bf16 v[44:47], v[182:185], v[190:193], v[44:47]
	v_mfma_f32_16x16x32_bf16 v[36:39], v[172:175], v[198:201], v[36:39]
	v_mfma_f32_16x16x32_bf16 v[28:31], v[182:185], v[198:201], v[28:31]
	v_mfma_f32_16x16x32_bf16 v[20:23], v[172:175], v[206:209], v[20:23]
	v_mfma_f32_16x16x32_bf16 v[12:15], v[182:185], v[206:209], v[12:15]
	v_mfma_f32_16x16x32_bf16 v[4:7], v[172:175], v[214:217], v[4:7]
	v_mfma_f32_16x16x32_bf16 v[0:3], v[182:185], v[214:217], v[0:3]
	s_barrier
	s_add_i32 s54, 0, 0x18000
	v_add_u32_e32 v159, s54, v154
	s_add_i32 s55, 0, 0x1c000
	ds_read_b128 v[144:147], v159
	ds_read_b128 v[148:151], v159 offset:1024
	ds_read_b128 v[160:163], v159 offset:2048
	ds_read_b128 v[164:167], v159 offset:3072
	v_add_u32_e32 v159, s55, v154
	ds_read_b128 v[168:171], v159
	ds_read_b128 v[172:175], v159 offset:1024
	ds_read_b128 v[176:179], v159 offset:2048
	ds_read_b128 v[182:185], v159 offset:3072
	s_add_u32 s26, s30, 0xb0000
	s_addc_u32 s27, s31, 0
	s_mov_b32 m0, s36
	v_lshl_add_u64 v[226:227], s[26:27], 0, v[128:129]
	ds_read_b128 v[186:189], v158 offset:32768
	ds_read_b128 v[190:193], v158 offset:33792
	ds_read_b128 v[194:197], v158 offset:34816
	ds_read_b128 v[198:201], v158 offset:35840
	ds_read_b128 v[202:205], v158 offset:36864
	ds_read_b128 v[206:209], v158 offset:37888
	ds_read_b128 v[210:213], v158 offset:38912
	ds_read_b128 v[214:217], v158 offset:39936
	global_load_lds_dwordx4 v[226:227], off
	v_lshl_add_u64 v[226:227], s[26:27], 0, v[132:133]
	s_mov_b32 m0, s37
	s_nop 0
	global_load_lds_dwordx4 v[226:227], off
	s_waitcnt vmcnt(8)
	s_waitcnt lgkmcnt(0)
	s_barrier
; #define PG8_STAGE(bufoff, gbase, voff) do { _Pragma("unroll") for (int _i = 0; _i < 2; ++_i) \
;         __builtin_amdgcn_global_load_lds((const unsigned*)((const char*)(gbase) + (voff)[_i]), (LAS unsigned*)(lds + (bufoff) + ldsw + _i * 8192), 16, 0, 0); } while (0)
; #define PG8_LDA(dst, b, h) do { _Pragma("unroll") for (int m = 0; m < 4; ++m) _Pragma("unroll") for (int k = 0; k < 2; ++k) dst[m][k] = *(const LAS bf16x8*)(lds + PG8_SA(b, h) + aoff + m * 2048 + k * 1024); } while (0)
; #define PG8_MMA(ai, bj, At, Bt) do { __builtin_amdgcn_s_setprio(1); _Pragma("unroll") for (int m = 0; m < 4; ++m) _Pragma("unroll") for (int n = 0; n < 2; ++n) _Pragma("unroll") for (int k = 0; k < 2; ++k) \
;         acc[ai][bj][m][n] = __builtin_amdgcn_mfma_f32_16x16x32_bf16(Bt[n][k], At[m][k], acc[ai][bj][m][n], 0, 0, 0); __builtin_amdgcn_s_setprio(0); } while (0)
; #define PG8_WAIT_V(n) asm volatile("s_waitcnt vmcnt(" #n ")" ::: "memory")
; #define PG8_WAIT_L(n) asm volatile("s_waitcnt lgkmcnt(" #n ")" ::: "memory")
; #define PG8_BAR __builtin_amdgcn_s_barrier()
; #define PG8_SCHED __builtin_amdgcn_sched_barrier(0)
; template <class Epi, class Sched, bool ALIGN_EPI = true>
; __device__ __forceinline__ void gemm_phase(LAS unsigned char* lds, const Gemm g, const Sched& S, const Epi& E) {
;     ...
;             PG8_WAIT_V(8); PG8_WAIT_L(0); PG8_BAR; PG8_MMA(0, 0, At, B0); PG8_MMA(0, 1, At, B1); PG8_BAR; PG8_SCHED;
;             PG8_LDA(At, 1, 1); PG8_STAGE(PG8_SB(1, 0), b3, voffB); PG8_STAGE(PG8_SB(1, 1), b3 + hsB, voffB); PG8_STAGE(PG8_SA(1, 0), a3, voffA);
;             PG8_WAIT_V(8); PG8_WAIT_L(0); PG8_BAR; PG8_MMA(1, 0, At, B0); PG8_MMA(1, 1, At, B1); PG8_BAR; PG8_SCHED;
;         }
;         if constexpr (ALIGN_EPI) { if (wr == 0) PG8_BAR; }
	s_waitcnt lgkmcnt(0)
	v_mfma_f32_16x16x32_bf16 v[124:127], v[144:147], v[186:189], v[124:127]
	v_mfma_f32_16x16x32_bf16 v[120:123], v[160:163], v[186:189], v[120:123]
	v_mfma_f32_16x16x32_bf16 v[112:115], v[144:147], v[194:197], v[112:115]
	v_mfma_f32_16x16x32_bf16 v[104:107], v[160:163], v[194:197], v[104:107]
	v_mfma_f32_16x16x32_bf16 v[96:99], v[144:147], v[202:205], v[96:99]
	v_mfma_f32_16x16x32_bf16 v[88:91], v[160:163], v[202:205], v[88:91]
	v_mfma_f32_16x16x32_bf16 v[80:83], v[144:147], v[210:213], v[80:83]
	v_mfma_f32_16x16x32_bf16 v[72:75], v[160:163], v[210:213], v[72:75]
	v_mfma_f32_16x16x32_bf16 v[124:127], v[148:151], v[190:193], v[124:127]
	v_mfma_f32_16x16x32_bf16 v[120:123], v[164:167], v[190:193], v[120:123]
	v_mfma_f32_16x16x32_bf16 v[112:115], v[148:151], v[198:201], v[112:115]
	v_mfma_f32_16x16x32_bf16 v[104:107], v[164:167], v[198:201], v[104:107]
	v_mfma_f32_16x16x32_bf16 v[96:99], v[148:151], v[206:209], v[96:99]
	v_mfma_f32_16x16x32_bf16 v[88:91], v[164:167], v[206:209], v[88:91]
	v_mfma_f32_16x16x32_bf16 v[80:83], v[148:151], v[214:217], v[80:83]
	v_mfma_f32_16x16x32_bf16 v[72:75], v[164:167], v[214:217], v[72:75]
	v_mfma_f32_16x16x32_bf16 v[116:119], v[168:171], v[186:189], v[116:119]
	v_mfma_f32_16x16x32_bf16 v[108:111], v[176:179], v[186:189], v[108:111]
	v_mfma_f32_16x16x32_bf16 v[100:103], v[168:171], v[194:197], v[100:103]
	v_mfma_f32_16x16x32_bf16 v[92:95], v[176:179], v[194:197], v[92:95]
	v_mfma_f32_16x16x32_bf16 v[84:87], v[168:171], v[202:205], v[84:87]
	v_mfma_f32_16x16x32_bf16 v[76:79], v[176:179], v[202:205], v[76:79]
	v_mfma_f32_16x16x32_bf16 v[68:71], v[168:171], v[210:213], v[68:71]
	v_mfma_f32_16x16x32_bf16 v[64:67], v[176:179], v[210:213], v[64:67]
	v_mfma_f32_16x16x32_bf16 v[116:119], v[172:175], v[190:193], v[116:119]
	v_mfma_f32_16x16x32_bf16 v[108:111], v[182:185], v[190:193], v[108:111]
	v_mfma_f32_16x16x32_bf16 v[100:103], v[172:175], v[198:201], v[100:103]
	v_mfma_f32_16x16x32_bf16 v[92:95], v[182:185], v[198:201], v[92:95]
	v_mfma_f32_16x16x32_bf16 v[84:87], v[172:175], v[206:209], v[84:87]
	v_mfma_f32_16x16x32_bf16 v[76:79], v[182:185], v[206:209], v[76:79]
	v_mfma_f32_16x16x32_bf16 v[68:71], v[172:175], v[214:217], v[68:71]
	v_mfma_f32_16x16x32_bf16 v[64:67], v[182:185], v[214:217], v[64:67]
	s_barrier
	s_add_i32 s26, s54, s33
	v_lshl_add_u64 v[218:219], v[218:219], 0, s[8:9]
	s_mov_b32 m0, s26
	ds_read_b128 v[186:189], v158 offset:49152
	ds_read_b128 v[190:193], v158 offset:50176
	ds_read_b128 v[194:197], v158 offset:51200
	ds_read_b128 v[198:201], v158 offset:52224
	ds_read_b128 v[202:205], v158 offset:53248
	ds_read_b128 v[206:209], v158 offset:54272
	ds_read_b128 v[210:213], v158 offset:55296
	ds_read_b128 v[214:217], v158 offset:56320
	global_load_lds_dwordx4 v[218:219], off
	s_add_i32 m0, s26, 0x2000
	s_add_u32 s26, s28, 0xb0080
	v_lshl_add_u64 v[218:219], v[220:221], 0, s[8:9]
	s_addc_u32 s27, s29, 0
	s_add_i32 s28, s55, s33
	global_load_lds_dwordx4 v[218:219], off
	v_lshl_add_u64 v[218:219], s[26:27], 0, v[130:131]
	s_mov_b32 m0, s28
	s_nop 0
	global_load_lds_dwordx4 v[218:219], off
	v_lshl_add_u64 v[218:219], s[26:27], 0, v[134:135]
	s_add_i32 m0, s28, 0x2000
	s_nop 0
	global_load_lds_dwordx4 v[218:219], off
	v_lshl_add_u64 v[218:219], v[222:223], 0, s[8:9]
	s_mov_b32 m0, s40
	s_nop 0
	global_load_lds_dwordx4 v[218:219], off
	v_lshl_add_u64 v[218:219], v[224:225], 0, s[8:9]
	s_mov_b32 m0, s41
	s_nop 0
	global_load_lds_dwordx4 v[218:219], off
	s_waitcnt vmcnt(8)
	s_waitcnt lgkmcnt(0)
	s_barrier
	s_waitcnt lgkmcnt(0)
	v_mfma_f32_16x16x32_bf16 v[60:63], v[144:147], v[186:189], v[60:63]
	v_mfma_f32_16x16x32_bf16 v[56:59], v[160:163], v[186:189], v[56:59]
	v_mfma_f32_16x16x32_bf16 v[48:51], v[144:147], v[194:197], v[48:51]
	v_mfma_f32_16x16x32_bf16 v[40:43], v[160:163], v[194:197], v[40:43]
	v_mfma_f32_16x16x32_bf16 v[32:35], v[144:147], v[202:205], v[32:35]
	v_mfma_f32_16x16x32_bf16 v[24:27], v[160:163], v[202:205], v[24:27]
	v_mfma_f32_16x16x32_bf16 v[16:19], v[144:147], v[210:213], v[16:19]
	v_mfma_f32_16x16x32_bf16 v[8:11], v[160:163], v[210:213], v[8:11]
	v_mfma_f32_16x16x32_bf16 v[60:63], v[148:151], v[190:193], v[60:63]
	v_mfma_f32_16x16x32_bf16 v[56:59], v[164:167], v[190:193], v[56:59]
	v_mfma_f32_16x16x32_bf16 v[48:51], v[148:151], v[198:201], v[48:51]
	v_mfma_f32_16x16x32_bf16 v[40:43], v[164:167], v[198:201], v[40:43]
	v_mfma_f32_16x16x32_bf16 v[32:35], v[148:151], v[206:209], v[32:35]
	v_mfma_f32_16x16x32_bf16 v[24:27], v[164:167], v[206:209], v[24:27]
	v_mfma_f32_16x16x32_bf16 v[16:19], v[148:151], v[214:217], v[16:19]
	v_mfma_f32_16x16x32_bf16 v[8:11], v[164:167], v[214:217], v[8:11]
	v_mfma_f32_16x16x32_bf16 v[52:55], v[168:171], v[186:189], v[52:55]
	v_mfma_f32_16x16x32_bf16 v[44:47], v[176:179], v[186:189], v[44:47]
	v_mfma_f32_16x16x32_bf16 v[36:39], v[168:171], v[194:197], v[36:39]
	v_mfma_f32_16x16x32_bf16 v[28:31], v[176:179], v[194:197], v[28:31]
	v_mfma_f32_16x16x32_bf16 v[20:23], v[168:171], v[202:205], v[20:23]
	v_mfma_f32_16x16x32_bf16 v[12:15], v[176:179], v[202:205], v[12:15]
	v_mfma_f32_16x16x32_bf16 v[4:7], v[168:171], v[210:213], v[4:7]
	v_mfma_f32_16x16x32_bf16 v[0:3], v[176:179], v[210:213], v[0:3]
	v_mfma_f32_16x16x32_bf16 v[52:55], v[172:175], v[190:193], v[52:55]
	v_mfma_f32_16x16x32_bf16 v[44:47], v[182:185], v[190:193], v[44:47]
	v_mfma_f32_16x16x32_bf16 v[36:39], v[172:175], v[198:201], v[36:39]
	v_mfma_f32_16x16x32_bf16 v[28:31], v[182:185], v[198:201], v[28:31]
	v_mfma_f32_16x16x32_bf16 v[20:23], v[172:175], v[206:209], v[20:23]
	v_mfma_f32_16x16x32_bf16 v[12:15], v[182:185], v[206:209], v[12:15]
	v_mfma_f32_16x16x32_bf16 v[4:7], v[172:175], v[214:217], v[4:7]
	v_mfma_f32_16x16x32_bf16 v[0:3], v[182:185], v[214:217], v[0:3]
	s_barrier
	s_add_i32 s53, s53, 2
	s_add_u32 s51, s51, 0x100
	s_addc_u32 s52, s52, 0
	s_cmp_gt_u32 s53, 41
	s_mov_b64 s[26:27], s[4:5]
	s_cbranch_scc0 .LBB0_999
	s_setprio 0
	s_and_b64 vcc, exec, s[12:13]
	s_cbranch_vccz .LBB0_1002
	s_barrier
